# nt (non-temporal) cache hint on the stream-once accesses of MIX1: sample-retention state loads/stores and the window-copy stores
# speedup vs baseline: 1.0237x; 1.0137x over previous
.LBB0_1017:
	s_and_b32 s82, s81, 7
	v_cvt_f32_ubyte0_e32 v0, s82
	v_sub_f32_e32 v0, 0xc0a00000, v0
	v_cmp_gt_f32_e64 s[16:17], s30, v0
	s_nop 1
	v_cndmask_b32_e64 v1, 0, v157, s[16:17]
	v_add_f32_e32 v0, v0, v1
	v_exp_f32_e32 v0, v0
	s_and_b64 s[16:17], s[16:17], exec
	s_cselect_b32 s2, 0xffffffc0, 0
	v_ldexp_f32 v0, v0, s2
	v_sub_f32_e32 v0, 1.0, v0
	v_cmp_gt_f32_e64 s[16:17], s31, v0
	s_nop 1
	v_cndmask_b32_e64 v1, 0, v158, s[16:17]
	s_and_b64 s[16:17], s[16:17], exec
	s_cselect_b32 s2, 32, 0
	v_ldexp_f32 v0, v0, s2
	v_log_f32_e32 v0, v0
	s_and_b32 s2, s81, -8
	s_add_i32 s18, s2, 0x2000
	s_ashr_i32 s19, s18, 31
	s_lshl_b32 s2, s82, 8
	v_sub_f32_e32 v12, v0, v1
	v_lshl_add_u64 v[0:1], v[106:107], 0, s[2:3]
	v_or_b32_e32 v2, s18, v96
	v_lshl_add_u64 v[4:5], s[18:19], 0, v[100:101]
	v_mul_f32_e32 v6, 0x41000000, v12
	v_mad_i64_i32 v[2:3], s[16:17], v2, s35, v[0:1]
	v_mad_u64_u32 v[0:1], s[16:17], v4, s35, v[0:1]
	v_cmp_gt_f32_e64 s[16:17], s30, v6
	v_mad_i32_i24 v1, v5, s35, v1
	v_lshl_add_u64 v[112:113], s[18:19], 0, v[102:103]
	v_cndmask_b32_e64 v4, 0, v157, s[16:17]
	v_fmac_f32_e32 v4, 0x41000000, v12
	v_exp_f32_e32 v4, v4
	s_and_b64 s[16:17], s[16:17], exec
	s_cselect_b32 s16, 0xffffffc0, 0
	v_lshl_add_u64 v[6:7], v[108:109], 0, v[104:105]
	v_ldexp_f32 v116, v4, s16
	v_mov_b64_e32 v[4:5], s[26:27]
	v_mad_u64_u32 v[114:115], s[16:17], v112, s35, v[4:5]
	v_mad_i32_i24 v115, v113, s35, v115
	s_lshl_b32 s16, s82, 9
	s_mov_b32 s17, s3
	v_lshl_add_u64 v[4:5], v[114:115], 0, s[16:17]
	v_lshl_add_u64 v[4:5], v[4:5], 0, v[98:99]
	v_add_co_u32_e64 v4, s[16:17], s52, v4
	v_mul_f32_e32 v13, 0xc1000000, v12
	s_nop 0
	v_addc_co_u32_e64 v5, s[16:17], 0, v5, s[16:17]
	v_add_co_u32_e64 v8, s[16:17], s33, v6
	s_nop 1
	v_addc_co_u32_e64 v9, s[16:17], 0, v7, s[16:17]
	s_movk_i32 s16, 0x4000
	global_load_dwordx4 v[92:95], v[6:7], off nt
	global_load_dwordx4 v[88:91], v[8:9], off nt
	v_add_co_u32_e64 v8, s[16:17], s16, v6
	s_nop 1
	v_addc_co_u32_e64 v9, s[16:17], 0, v7, s[16:17]
	s_movk_i32 s16, 0x6000
	s_nop 0
	v_add_co_u32_e64 v10, s[16:17], s16, v6
	s_nop 1
	v_addc_co_u32_e64 v11, s[16:17], 0, v7, s[16:17]
	global_load_dwordx4 v[84:87], v[8:9], off nt
	global_load_dwordx4 v[76:79], v[10:11], off nt
	s_nop 0
	global_load_dwordx2 v[4:5], v[4:5], off offset:3072
	s_nop 0
	global_load_ushort v10, v[2:3], off offset:3072
	v_add_co_u32_e64 v8, s[16:17], s53, v6
	s_nop 1
	v_addc_co_u32_e64 v9, s[16:17], 0, v7, s[16:17]
	v_add_co_u32_e64 v2, s[16:17], s52, v2
	s_nop 1
	v_addc_co_u32_e64 v3, s[16:17], 0, v3, s[16:17]
	global_load_ushort v11, v[2:3], off offset:1024
	v_add_co_u32_e64 v2, s[16:17], s54, v6
	s_nop 1
	v_addc_co_u32_e64 v3, s[16:17], 0, v7, s[16:17]
	global_load_dwordx4 v[80:83], v[8:9], off nt
	global_load_dwordx4 v[72:75], v[2:3], off nt
	v_add_co_u32_e64 v2, s[16:17], s55, v6
	global_load_ushort v14, v[0:1], off offset:3072
	s_nop 0
	v_addc_co_u32_e64 v3, s[16:17], 0, v7, s[16:17]
	v_add_co_u32_e64 v8, s[16:17], s56, v6
	s_nop 1
	v_addc_co_u32_e64 v9, s[16:17], 0, v7, s[16:17]
	v_add_co_u32_e64 v0, s[16:17], s52, v0
	s_nop 1
	v_addc_co_u32_e64 v1, s[16:17], 0, v1, s[16:17]
	global_load_ushort v15, v[0:1], off offset:1024
	global_load_dwordx4 v[68:71], v[2:3], off nt
	global_load_dwordx4 v[64:67], v[8:9], off nt
	v_add_co_u32_e64 v0, s[16:17], s57, v6
	s_nop 1
	v_addc_co_u32_e64 v1, s[16:17], 0, v7, s[16:17]
	v_add_co_u32_e64 v2, s[16:17], s58, v6
	s_nop 1
	v_addc_co_u32_e64 v3, s[16:17], 0, v7, s[16:17]
	global_load_dwordx4 v[60:63], v[0:1], off nt
	global_load_dwordx4 v[56:59], v[2:3], off nt
	v_add_co_u32_e64 v0, s[16:17], s59, v6
	s_nop 1
	v_addc_co_u32_e64 v1, s[16:17], 0, v7, s[16:17]
	v_add_co_u32_e64 v2, s[16:17], s60, v6
	s_nop 1
	v_addc_co_u32_e64 v3, s[16:17], 0, v7, s[16:17]
	global_load_dwordx4 v[52:55], v[0:1], off nt
	global_load_dwordx4 v[48:51], v[2:3], off nt
	v_add_co_u32_e64 v0, s[16:17], s61, v6
	s_nop 1
	v_addc_co_u32_e64 v1, s[16:17], 0, v7, s[16:17]
	v_add_co_u32_e64 v2, s[16:17], s62, v6
	s_nop 1
	v_addc_co_u32_e64 v3, s[16:17], 0, v7, s[16:17]
	global_load_dwordx4 v[44:47], v[0:1], off nt
	global_load_dwordx4 v[40:43], v[2:3], off nt
	v_add_co_u32_e64 v0, s[16:17], s63, v6
	s_nop 1
	v_addc_co_u32_e64 v1, s[16:17], 0, v7, s[16:17]
	v_add_co_u32_e64 v2, s[16:17], s64, v6
	s_nop 1
	v_addc_co_u32_e64 v3, s[16:17], 0, v7, s[16:17]
	global_load_dwordx4 v[36:39], v[0:1], off nt
	global_load_dwordx4 v[28:31], v[2:3], off nt
	v_mul_f32_e32 v1, v12, v97
	v_cmp_gt_f32_e64 s[18:19], s30, v1
	v_cmp_gt_f32_e64 s[16:17], s30, v13
	s_nop 0
	v_cndmask_b32_e64 v1, 0, v157, s[18:19]
	v_fmac_f32_e32 v1, v12, v97
	v_exp_f32_e32 v1, v1
	v_cndmask_b32_e64 v2, 0, v159, s[18:19]
	v_cndmask_b32_e64 v0, 0, v157, s[16:17]
	v_fmac_f32_e32 v0, 0xc1000000, v12
	v_ldexp_f32 v1, v1, v2
	v_mul_f32_e32 v2, v12, v120
	v_cmp_gt_f32_e64 s[18:19], s30, v2
	v_exp_f32_e32 v160, v0
	s_waitcnt vmcnt(15)
	v_lshlrev_b32_e32 v0, 16, v10
	v_cndmask_b32_e64 v2, 0, v157, s[18:19]
	v_fmac_f32_e32 v2, v12, v120
	v_exp_f32_e32 v2, v2
	v_cndmask_b32_e64 v3, 0, v159, s[18:19]
	v_mul_f32_e32 v0, v1, v0
	s_waitcnt vmcnt(14)
	v_lshlrev_b32_e32 v1, 16, v11
	v_ldexp_f32 v2, v2, v3
	v_mul_f32_e32 v1, v2, v1
	v_mul_f32_e32 v2, v12, v121
	v_cmp_gt_f32_e64 s[18:19], s30, v2
	ds_write2st64_b32 v117, v0, v1 offset1:16
	s_waitcnt vmcnt(11)
	v_lshlrev_b32_e32 v0, 16, v14
	v_cndmask_b32_e64 v2, 0, v157, s[18:19]
	v_fmac_f32_e32 v2, v12, v121
	v_exp_f32_e32 v2, v2
	v_cndmask_b32_e64 v1, 0, v159, s[18:19]
	s_and_b64 s[16:17], s[16:17], exec
	v_ldexp_f32 v1, v2, v1
	v_mul_f32_e32 v2, v12, v123
	v_cmp_gt_f32_e64 s[18:19], s30, v2
	v_mul_f32_e32 v0, v1, v0
	s_waitcnt vmcnt(10)
	v_lshlrev_b32_e32 v1, 16, v15
	v_cndmask_b32_e64 v2, 0, v157, s[18:19]
	v_fmac_f32_e32 v2, v12, v123
	v_exp_f32_e32 v2, v2
	v_cndmask_b32_e64 v3, 0, v159, s[18:19]
	v_add_u32_e32 v12, 0x1000, v127
	s_cselect_b32 s18, 0xffffffc0, 0
	v_ldexp_f32 v2, v2, v3
	v_mul_f32_e32 v1, v2, v1
	ds_write2st64_b32 v122, v0, v1 offset1:16
	v_lshlrev_b32_e32 v0, 16, v4
	v_and_b32_e32 v1, 0xffff0000, v4
	v_lshlrev_b32_e32 v2, 16, v5
	v_and_b32_e32 v3, 0xffff0000, v5
	ds_write_b128 v125, v[0:3] offset:8192
	s_waitcnt lgkmcnt(0)
	s_barrier
	ds_read2_b32 v[0:1], v126 offset1:8
	ds_read2_b32 v[2:3], v12 offset1:8
	ds_read2_b32 v[4:5], v126 offset0:16 offset1:24
	ds_read2_b32 v[6:7], v12 offset0:16 offset1:24
	s_waitcnt lgkmcnt(2)
	v_fma_f32 v13, v0, v2, 0
	v_fmac_f32_e32 v13, v1, v3
	s_waitcnt lgkmcnt(0)
	v_fmac_f32_e32 v13, v4, v6
	v_fmac_f32_e32 v13, v5, v7
	ds_read2_b32 v[0:1], v126 offset0:32 offset1:40
	ds_read2_b32 v[2:3], v12 offset0:32 offset1:40
	ds_read2_b32 v[4:5], v126 offset0:48 offset1:56
	ds_read2_b32 v[6:7], v12 offset0:48 offset1:56
	ds_read2_b32 v[8:9], v126 offset0:64 offset1:72
	ds_read2_b32 v[10:11], v12 offset0:64 offset1:72
	s_waitcnt lgkmcnt(4)
	v_fmac_f32_e32 v13, v0, v2
	v_fmac_f32_e32 v13, v1, v3
	s_waitcnt lgkmcnt(2)
	v_fmac_f32_e32 v13, v4, v6
	v_fmac_f32_e32 v13, v5, v7
	s_waitcnt lgkmcnt(0)
	v_fmac_f32_e32 v13, v8, v10
	v_fmac_f32_e32 v13, v9, v11
	ds_read2_b32 v[0:1], v126 offset0:80 offset1:88
	ds_read2_b32 v[2:3], v12 offset0:80 offset1:88
	ds_read2_b32 v[4:5], v126 offset0:96 offset1:104
	ds_read2_b32 v[6:7], v12 offset0:96 offset1:104
	ds_read2_b32 v[8:9], v126 offset0:112 offset1:120
	ds_read2_b32 v[10:11], v12 offset0:112 offset1:120
	s_waitcnt lgkmcnt(4)
	v_fmac_f32_e32 v13, v0, v2
	v_fmac_f32_e32 v13, v1, v3
	s_waitcnt lgkmcnt(2)
	v_fmac_f32_e32 v13, v4, v6
	v_fmac_f32_e32 v13, v5, v7
	s_waitcnt lgkmcnt(0)
	v_fmac_f32_e32 v13, v8, v10
	v_fmac_f32_e32 v13, v9, v11
	ds_write_b32 v129, v13 offset:16384
	ds_read_b128 v[32:35], v124 offset:8192
	ds_read_b128 v[24:27], v124 offset:9216
	ds_read_b128 v[20:23], v124 offset:10240
	ds_read_b128 v[16:19], v124 offset:11264
	ds_read_b128 v[12:15], v124 offset:12288
	ds_read_b128 v[8:11], v124 offset:13312
	ds_read_b128 v[162:165], v130 offset:4096
	ds_read_b128 v[4:7], v124 offset:14336
	ds_read_b128 v[0:3], v124 offset:15360
	ds_read_b128 v[166:169], v130
	ds_read_b128 v[170:173], v130 offset:16
	ds_read_b128 v[174:177], v130 offset:4112
	s_waitcnt lgkmcnt(5)
	v_pk_mul_f32 v[118:119], v[34:35], v[162:163] op_sel_hi:[1,0]
	v_pk_mul_f32 v[178:179], v[32:33], v[162:163] op_sel_hi:[1,0]
	v_pk_fma_f32 v[118:119], v[94:95], v[116:117], v[118:119] op_sel_hi:[1,0,1]
	v_pk_fma_f32 v[178:179], v[92:93], v[116:117], v[178:179] op_sel_hi:[1,0,1]
	v_pk_fma_f32 v[118:119], v[26:27], v[162:163], v[118:119] op_sel:[0,1,0]
	v_pk_fma_f32 v[162:163], v[24:25], v[162:163], v[178:179] op_sel:[0,1,0]
	v_pk_fma_f32 v[118:119], v[22:23], v[164:165], v[118:119] op_sel_hi:[1,0,1]
	v_pk_fma_f32 v[162:163], v[20:21], v[164:165], v[162:163] op_sel_hi:[1,0,1]
	v_mov_b32_e32 v164, v165
	v_pk_fma_f32 v[118:119], v[18:19], v[164:165], v[118:119] op_sel_hi:[1,0,1]
	v_pk_fma_f32 v[162:163], v[16:17], v[164:165], v[162:163] op_sel_hi:[1,0,1]
	s_waitcnt lgkmcnt(0)
	v_pk_fma_f32 v[118:119], v[14:15], v[174:175], v[118:119] op_sel_hi:[1,0,1]
	v_pk_fma_f32 v[162:163], v[12:13], v[174:175], v[162:163] op_sel_hi:[1,0,1]
	v_pk_fma_f32 v[118:119], v[10:11], v[174:175], v[118:119] op_sel:[0,1,0]
	v_pk_fma_f32 v[162:163], v[8:9], v[174:175], v[162:163] op_sel:[0,1,0]
	v_pk_fma_f32 v[118:119], v[6:7], v[176:177], v[118:119] op_sel_hi:[1,0,1]
	v_mov_b32_e32 v174, v177
	v_pk_fma_f32 v[162:163], v[4:5], v[176:177], v[162:163] op_sel_hi:[1,0,1]
	v_pk_fma_f32 v[164:165], v[2:3], v[174:175], v[118:119] op_sel_hi:[1,0,1]
	v_lshl_add_u64 v[118:119], v[110:111], 0, v[104:105]
	v_pk_fma_f32 v[162:163], v[0:1], v[174:175], v[162:163] op_sel_hi:[1,0,1]
	v_add_co_u32_e64 v174, s[16:17], s65, v118
	v_pk_fma_f32 v[176:177], v[92:93], v[166:167], 0 op_sel_hi:[1,0,0]
	s_nop 0
	v_addc_co_u32_e64 v175, s[16:17], 0, v119, s[16:17]
	global_store_dwordx4 v[174:175], v[162:165], off nt
	v_pk_fma_f32 v[174:175], v[94:95], v[166:167], 0 op_sel_hi:[1,0,0]
	v_pk_fma_f32 v[178:179], v[94:95], v[166:167], 0 op_sel:[0,1,0] op_sel_hi:[1,1,0]
	v_mov_b32_e32 v162, v169
	v_pk_fma_f32 v[186:187], v[94:95], v[162:163], 0 op_sel_hi:[1,0,0]
	v_pk_fma_f32 v[188:189], v[92:93], v[162:163], 0 op_sel_hi:[1,0,0]
	ds_read_b128 v[162:165], v131 offset:4096
	v_pk_fma_f32 v[180:181], v[92:93], v[166:167], 0 op_sel:[0,1,0] op_sel_hi:[1,1,0]
	v_mov_b32_e32 v166, v173
	v_pk_fma_f32 v[182:183], v[94:95], v[168:169], 0 op_sel_hi:[1,0,0]
	v_pk_fma_f32 v[184:185], v[92:93], v[168:169], 0 op_sel_hi:[1,0,0]
	v_pk_fma_f32 v[190:191], v[94:95], v[170:171], 0 op_sel_hi:[1,0,0]
	v_pk_fma_f32 v[192:193], v[92:93], v[170:171], 0 op_sel_hi:[1,0,0]
	v_pk_fma_f32 v[194:195], v[94:95], v[170:171], 0 op_sel:[0,1,0] op_sel_hi:[1,1,0]
	v_pk_fma_f32 v[196:197], v[92:93], v[170:171], 0 op_sel:[0,1,0] op_sel_hi:[1,1,0]
	v_pk_fma_f32 v[198:199], v[94:95], v[172:173], 0 op_sel_hi:[1,0,0]
	v_pk_fma_f32 v[200:201], v[92:93], v[172:173], 0 op_sel_hi:[1,0,0]
	v_pk_fma_f32 v[202:203], v[94:95], v[166:167], 0 op_sel_hi:[1,0,0]
	v_pk_fma_f32 v[204:205], v[92:93], v[166:167], 0 op_sel_hi:[1,0,0]
	ds_read_b128 v[92:95], v131
	ds_read_b128 v[166:169], v131 offset:16
	ds_read_b128 v[170:173], v131 offset:4112
	s_waitcnt lgkmcnt(3)
	v_pk_mul_f32 v[206:207], v[34:35], v[162:163] op_sel_hi:[1,0]
	v_pk_mul_f32 v[208:209], v[32:33], v[162:163] op_sel_hi:[1,0]
	v_pk_fma_f32 v[206:207], v[90:91], v[116:117], v[206:207] op_sel_hi:[1,0,1]
	v_pk_fma_f32 v[208:209], v[88:89], v[116:117], v[208:209] op_sel_hi:[1,0,1]
	v_pk_fma_f32 v[206:207], v[26:27], v[162:163], v[206:207] op_sel:[0,1,0]
	v_pk_fma_f32 v[162:163], v[24:25], v[162:163], v[208:209] op_sel:[0,1,0]
	v_pk_fma_f32 v[206:207], v[22:23], v[164:165], v[206:207] op_sel_hi:[1,0,1]
	v_pk_fma_f32 v[162:163], v[20:21], v[164:165], v[162:163] op_sel_hi:[1,0,1]
	v_mov_b32_e32 v164, v165
	v_pk_fma_f32 v[206:207], v[18:19], v[164:165], v[206:207] op_sel_hi:[1,0,1]
	v_pk_fma_f32 v[162:163], v[16:17], v[164:165], v[162:163] op_sel_hi:[1,0,1]
	s_waitcnt lgkmcnt(0)
	v_pk_fma_f32 v[164:165], v[14:15], v[170:171], v[206:207] op_sel_hi:[1,0,1]
	v_pk_fma_f32 v[162:163], v[12:13], v[170:171], v[162:163] op_sel_hi:[1,0,1]
	v_pk_fma_f32 v[164:165], v[10:11], v[170:171], v[164:165] op_sel:[0,1,0]
	v_pk_fma_f32 v[162:163], v[8:9], v[170:171], v[162:163] op_sel:[0,1,0]
	v_pk_fma_f32 v[164:165], v[6:7], v[172:173], v[164:165] op_sel_hi:[1,0,1]
	v_pk_fma_f32 v[162:163], v[4:5], v[172:173], v[162:163] op_sel_hi:[1,0,1]
	v_mov_b32_e32 v170, v173
	v_pk_fma_f32 v[164:165], v[2:3], v[170:171], v[164:165] op_sel_hi:[1,0,1]
	v_pk_fma_f32 v[162:163], v[0:1], v[170:171], v[162:163] op_sel_hi:[1,0,1]
	v_add_co_u32_e64 v170, s[16:17], s66, v118
	v_pk_fma_f32 v[172:173], v[88:89], v[92:93], v[176:177] op_sel_hi:[1,0,1]
	s_nop 0
	v_addc_co_u32_e64 v171, s[16:17], 0, v119, s[16:17]
	global_store_dwordx4 v[170:171], v[162:165], off nt
	v_pk_fma_f32 v[170:171], v[90:91], v[92:93], v[174:175] op_sel_hi:[1,0,1]
	v_pk_fma_f32 v[174:175], v[90:91], v[92:93], v[178:179] op_sel:[0,1,0]
	v_pk_fma_f32 v[176:177], v[88:89], v[92:93], v[180:181] op_sel:[0,1,0]
	v_mov_b32_e32 v92, v95
	v_pk_fma_f32 v[178:179], v[88:89], v[94:95], v[184:185] op_sel_hi:[1,0,1]
	v_pk_fma_f32 v[180:181], v[90:91], v[94:95], v[182:183] op_sel_hi:[1,0,1]
	v_pk_fma_f32 v[182:183], v[88:89], v[92:93], v[188:189] op_sel_hi:[1,0,1]
	v_pk_fma_f32 v[184:185], v[90:91], v[92:93], v[186:187] op_sel_hi:[1,0,1]
	ds_read_b128 v[92:95], v132 offset:4096
	v_mov_b32_e32 v162, v169
	v_pk_fma_f32 v[186:187], v[90:91], v[166:167], v[190:191] op_sel_hi:[1,0,1]
	v_pk_fma_f32 v[188:189], v[88:89], v[166:167], v[192:193] op_sel_hi:[1,0,1]
	v_pk_fma_f32 v[190:191], v[90:91], v[166:167], v[194:195] op_sel:[0,1,0]
	v_pk_fma_f32 v[192:193], v[88:89], v[166:167], v[196:197] op_sel:[0,1,0]
	v_pk_fma_f32 v[194:195], v[88:89], v[168:169], v[200:201] op_sel_hi:[1,0,1]
	v_pk_fma_f32 v[196:197], v[90:91], v[168:169], v[198:199] op_sel_hi:[1,0,1]
	v_pk_fma_f32 v[198:199], v[88:89], v[162:163], v[204:205] op_sel_hi:[1,0,1]
	v_pk_fma_f32 v[200:201], v[90:91], v[162:163], v[202:203] op_sel_hi:[1,0,1]
	ds_read_b128 v[88:91], v132
	ds_read_b128 v[162:165], v132 offset:16
	ds_read_b128 v[166:169], v132 offset:4112
	s_waitcnt lgkmcnt(3)
	v_pk_mul_f32 v[202:203], v[34:35], v[92:93] op_sel_hi:[1,0]
	v_pk_mul_f32 v[204:205], v[32:33], v[92:93] op_sel_hi:[1,0]
	v_pk_fma_f32 v[202:203], v[86:87], v[116:117], v[202:203] op_sel_hi:[1,0,1]
	v_pk_fma_f32 v[204:205], v[84:85], v[116:117], v[204:205] op_sel_hi:[1,0,1]
	v_pk_fma_f32 v[202:203], v[26:27], v[92:93], v[202:203] op_sel:[0,1,0]
	v_pk_fma_f32 v[92:93], v[24:25], v[92:93], v[204:205] op_sel:[0,1,0]
	v_pk_fma_f32 v[202:203], v[22:23], v[94:95], v[202:203] op_sel_hi:[1,0,1]
	v_pk_fma_f32 v[92:93], v[20:21], v[94:95], v[92:93] op_sel_hi:[1,0,1]
	v_mov_b32_e32 v94, v95
	v_pk_fma_f32 v[202:203], v[18:19], v[94:95], v[202:203] op_sel_hi:[1,0,1]
	v_pk_fma_f32 v[92:93], v[16:17], v[94:95], v[92:93] op_sel_hi:[1,0,1]
	s_waitcnt lgkmcnt(0)
	v_pk_fma_f32 v[94:95], v[14:15], v[166:167], v[202:203] op_sel_hi:[1,0,1]
	v_pk_fma_f32 v[92:93], v[12:13], v[166:167], v[92:93] op_sel_hi:[1,0,1]
	v_pk_fma_f32 v[94:95], v[10:11], v[166:167], v[94:95] op_sel:[0,1,0]
	v_pk_fma_f32 v[92:93], v[8:9], v[166:167], v[92:93] op_sel:[0,1,0]
	v_pk_fma_f32 v[94:95], v[6:7], v[168:169], v[94:95] op_sel_hi:[1,0,1]
	v_pk_fma_f32 v[92:93], v[4:5], v[168:169], v[92:93] op_sel_hi:[1,0,1]
	v_mov_b32_e32 v166, v169
	v_pk_fma_f32 v[94:95], v[2:3], v[166:167], v[94:95] op_sel_hi:[1,0,1]
	v_pk_fma_f32 v[92:93], v[0:1], v[166:167], v[92:93] op_sel_hi:[1,0,1]
	v_add_co_u32_e64 v166, s[16:17], s67, v118
	v_pk_fma_f32 v[178:179], v[84:85], v[90:91], v[178:179] op_sel_hi:[1,0,1]
	s_nop 0
	v_addc_co_u32_e64 v167, s[16:17], 0, v119, s[16:17]
	global_store_dwordx4 v[166:167], v[92:95], off nt
	v_pk_fma_f32 v[194:195], v[84:85], v[164:165], v[194:195] op_sel_hi:[1,0,1]
	s_nop 0
	v_pk_fma_f32 v[94:95], v[86:87], v[88:89], v[170:171] op_sel_hi:[1,0,1]
	v_pk_fma_f32 v[170:171], v[84:85], v[88:89], v[172:173] op_sel_hi:[1,0,1]
	v_pk_fma_f32 v[172:173], v[86:87], v[88:89], v[174:175] op_sel:[0,1,0]
	v_pk_fma_f32 v[174:175], v[84:85], v[88:89], v[176:177] op_sel:[0,1,0]
	v_pk_fma_f32 v[176:177], v[86:87], v[90:91], v[180:181] op_sel_hi:[1,0,1]
	v_mov_b32_e32 v88, v91
	v_mov_b32_e32 v90, v165
	v_pk_fma_f32 v[180:181], v[86:87], v[88:89], v[184:185] op_sel_hi:[1,0,1]
	v_pk_fma_f32 v[182:183], v[84:85], v[88:89], v[182:183] op_sel_hi:[1,0,1]
	v_pk_fma_f32 v[184:185], v[86:87], v[162:163], v[186:187] op_sel_hi:[1,0,1]
	v_pk_fma_f32 v[186:187], v[84:85], v[162:163], v[188:189] op_sel_hi:[1,0,1]
	v_pk_fma_f32 v[188:189], v[86:87], v[162:163], v[190:191] op_sel:[0,1,0]
	v_pk_fma_f32 v[190:191], v[84:85], v[162:163], v[192:193] op_sel:[0,1,0]
	v_pk_fma_f32 v[192:193], v[86:87], v[164:165], v[196:197] op_sel_hi:[1,0,1]
	v_pk_fma_f32 v[196:197], v[86:87], v[90:91], v[200:201] op_sel_hi:[1,0,1]
	ds_read_b128 v[86:89], v133 offset:4096
	v_pk_fma_f32 v[198:199], v[84:85], v[90:91], v[198:199] op_sel_hi:[1,0,1]
	ds_read_b128 v[90:93], v133
	ds_read_b128 v[162:165], v133 offset:16
	ds_read_b128 v[166:169], v133 offset:4112
	s_waitcnt lgkmcnt(3)
	v_pk_mul_f32 v[84:85], v[34:35], v[86:87] op_sel_hi:[1,0]
	v_pk_mul_f32 v[200:201], v[32:33], v[86:87] op_sel_hi:[1,0]
	v_pk_fma_f32 v[84:85], v[78:79], v[116:117], v[84:85] op_sel_hi:[1,0,1]
	v_pk_fma_f32 v[200:201], v[76:77], v[116:117], v[200:201] op_sel_hi:[1,0,1]
	v_pk_fma_f32 v[84:85], v[26:27], v[86:87], v[84:85] op_sel:[0,1,0]
	v_pk_fma_f32 v[86:87], v[24:25], v[86:87], v[200:201] op_sel:[0,1,0]
	v_pk_fma_f32 v[84:85], v[22:23], v[88:89], v[84:85] op_sel_hi:[1,0,1]
	v_pk_fma_f32 v[86:87], v[20:21], v[88:89], v[86:87] op_sel_hi:[1,0,1]
	v_mov_b32_e32 v88, v89
	v_pk_fma_f32 v[84:85], v[18:19], v[88:89], v[84:85] op_sel_hi:[1,0,1]
	v_pk_fma_f32 v[86:87], v[16:17], v[88:89], v[86:87] op_sel_hi:[1,0,1]
	s_waitcnt lgkmcnt(0)
	v_pk_fma_f32 v[84:85], v[14:15], v[166:167], v[84:85] op_sel_hi:[1,0,1]
	v_pk_fma_f32 v[86:87], v[12:13], v[166:167], v[86:87] op_sel_hi:[1,0,1]
	v_pk_fma_f32 v[84:85], v[10:11], v[166:167], v[84:85] op_sel:[0,1,0]
	v_pk_fma_f32 v[86:87], v[8:9], v[166:167], v[86:87] op_sel:[0,1,0]
	v_pk_fma_f32 v[84:85], v[6:7], v[168:169], v[84:85] op_sel_hi:[1,0,1]
	v_pk_fma_f32 v[88:89], v[4:5], v[168:169], v[86:87] op_sel_hi:[1,0,1]
	v_mov_b32_e32 v166, v169
	v_pk_fma_f32 v[86:87], v[2:3], v[166:167], v[84:85] op_sel_hi:[1,0,1]
	v_pk_fma_f32 v[84:85], v[0:1], v[166:167], v[88:89] op_sel_hi:[1,0,1]
	v_add_co_u32_e64 v88, s[16:17], s68, v118
	v_pk_fma_f32 v[168:169], v[76:77], v[90:91], v[170:171] op_sel_hi:[1,0,1]
	s_nop 0
	v_addc_co_u32_e64 v89, s[16:17], 0, v119, s[16:17]
	global_store_dwordx4 v[88:89], v[84:87], off nt
	v_pk_fma_f32 v[170:171], v[78:79], v[90:91], v[172:173] op_sel:[0,1,0]
	v_pk_fma_f32 v[172:173], v[76:77], v[90:91], v[174:175] op_sel:[0,1,0]
	v_mov_b32_e32 v84, v93
	v_pk_fma_f32 v[174:175], v[78:79], v[92:93], v[176:177] op_sel_hi:[1,0,1]
	v_pk_fma_f32 v[176:177], v[76:77], v[92:93], v[178:179] op_sel_hi:[1,0,1]
	v_pk_fma_f32 v[178:179], v[78:79], v[84:85], v[180:181] op_sel_hi:[1,0,1]
	v_pk_fma_f32 v[180:181], v[76:77], v[84:85], v[182:183] op_sel_hi:[1,0,1]
	ds_read_b128 v[84:87], v134 offset:4096
	v_mov_b32_e32 v88, v165
	v_pk_fma_f32 v[166:167], v[78:79], v[90:91], v[94:95] op_sel_hi:[1,0,1]
	v_pk_fma_f32 v[182:183], v[78:79], v[162:163], v[184:185] op_sel_hi:[1,0,1]
	v_pk_fma_f32 v[184:185], v[76:77], v[162:163], v[186:187] op_sel_hi:[1,0,1]
	v_pk_fma_f32 v[186:187], v[78:79], v[162:163], v[188:189] op_sel:[0,1,0]
	v_pk_fma_f32 v[162:163], v[76:77], v[162:163], v[190:191] op_sel:[0,1,0]
	v_pk_fma_f32 v[188:189], v[78:79], v[164:165], v[192:193] op_sel_hi:[1,0,1]
	v_pk_fma_f32 v[190:191], v[76:77], v[164:165], v[194:195] op_sel_hi:[1,0,1]
	v_pk_fma_f32 v[164:165], v[78:79], v[88:89], v[196:197] op_sel_hi:[1,0,1]
	v_pk_fma_f32 v[192:193], v[76:77], v[88:89], v[198:199] op_sel_hi:[1,0,1]
	ds_read_b128 v[76:79], v134
	ds_read_b128 v[88:91], v134 offset:16
	ds_read_b128 v[92:95], v134 offset:4112
	s_waitcnt lgkmcnt(3)
	v_pk_mul_f32 v[194:195], v[34:35], v[84:85] op_sel_hi:[1,0]
	v_pk_mul_f32 v[196:197], v[32:33], v[84:85] op_sel_hi:[1,0]
	v_pk_fma_f32 v[194:195], v[116:117], v[82:83], v[194:195] op_sel_hi:[0,1,1]
	v_pk_fma_f32 v[196:197], v[116:117], v[80:81], v[196:197] op_sel_hi:[0,1,1]
	v_pk_fma_f32 v[194:195], v[26:27], v[84:85], v[194:195] op_sel:[0,1,0]
	v_pk_fma_f32 v[84:85], v[24:25], v[84:85], v[196:197] op_sel:[0,1,0]
	v_pk_fma_f32 v[194:195], v[22:23], v[86:87], v[194:195] op_sel_hi:[1,0,1]
	v_pk_fma_f32 v[84:85], v[20:21], v[86:87], v[84:85] op_sel_hi:[1,0,1]
	v_mov_b32_e32 v86, v87
	v_pk_fma_f32 v[194:195], v[18:19], v[86:87], v[194:195] op_sel_hi:[1,0,1]
	v_pk_fma_f32 v[84:85], v[16:17], v[86:87], v[84:85] op_sel_hi:[1,0,1]
	s_waitcnt lgkmcnt(0)
	v_pk_fma_f32 v[86:87], v[14:15], v[92:93], v[194:195] op_sel_hi:[1,0,1]
	v_pk_fma_f32 v[84:85], v[12:13], v[92:93], v[84:85] op_sel_hi:[1,0,1]
	v_pk_fma_f32 v[86:87], v[10:11], v[92:93], v[86:87] op_sel:[0,1,0]
	v_pk_fma_f32 v[84:85], v[8:9], v[92:93], v[84:85] op_sel:[0,1,0]
	v_pk_fma_f32 v[86:87], v[6:7], v[94:95], v[86:87] op_sel_hi:[1,0,1]
	v_pk_fma_f32 v[84:85], v[4:5], v[94:95], v[84:85] op_sel_hi:[1,0,1]
	v_mov_b32_e32 v92, v95
	v_pk_fma_f32 v[86:87], v[2:3], v[92:93], v[86:87] op_sel_hi:[1,0,1]
	v_pk_fma_f32 v[84:85], v[0:1], v[92:93], v[84:85] op_sel_hi:[1,0,1]
	v_add_co_u32_e64 v92, s[16:17], s69, v118
	v_pk_fma_f32 v[94:95], v[80:81], v[76:77], v[168:169] op_sel_hi:[1,0,1]
	s_nop 0
	v_addc_co_u32_e64 v93, s[16:17], 0, v119, s[16:17]
	global_store_dwordx4 v[92:93], v[84:87], off nt
	v_pk_fma_f32 v[92:93], v[82:83], v[76:77], v[166:167] op_sel_hi:[1,0,1]
	v_pk_fma_f32 v[166:167], v[82:83], v[76:77], v[170:171] op_sel:[0,1,0]
	v_pk_fma_f32 v[168:169], v[80:81], v[76:77], v[172:173] op_sel:[0,1,0]
	v_mov_b32_e32 v76, v79
	v_pk_fma_f32 v[170:171], v[82:83], v[78:79], v[174:175] op_sel_hi:[1,0,1]
	v_pk_fma_f32 v[172:173], v[80:81], v[78:79], v[176:177] op_sel_hi:[1,0,1]
	v_pk_fma_f32 v[174:175], v[82:83], v[76:77], v[178:179] op_sel_hi:[1,0,1]
	v_pk_fma_f32 v[176:177], v[80:81], v[76:77], v[180:181] op_sel_hi:[1,0,1]
	ds_read_b128 v[76:79], v135 offset:4096
	v_mov_b32_e32 v84, v91
	v_pk_fma_f32 v[178:179], v[82:83], v[88:89], v[182:183] op_sel_hi:[1,0,1]
	v_pk_fma_f32 v[180:181], v[80:81], v[88:89], v[184:185] op_sel_hi:[1,0,1]
	v_pk_fma_f32 v[182:183], v[82:83], v[88:89], v[186:187] op_sel:[0,1,0]
	v_pk_fma_f32 v[162:163], v[80:81], v[88:89], v[162:163] op_sel:[0,1,0]
	v_pk_fma_f32 v[184:185], v[82:83], v[90:91], v[188:189] op_sel_hi:[1,0,1]
	v_pk_fma_f32 v[186:187], v[80:81], v[90:91], v[190:191] op_sel_hi:[1,0,1]
	v_pk_fma_f32 v[164:165], v[82:83], v[84:85], v[164:165] op_sel_hi:[1,0,1]
	v_pk_fma_f32 v[188:189], v[80:81], v[84:85], v[192:193] op_sel_hi:[1,0,1]
	ds_read_b128 v[80:83], v135
	ds_read_b128 v[84:87], v135 offset:16
	ds_read_b128 v[88:91], v135 offset:4112
	s_waitcnt lgkmcnt(3)
	v_pk_mul_f32 v[190:191], v[34:35], v[76:77] op_sel_hi:[1,0]
	v_pk_mul_f32 v[192:193], v[32:33], v[76:77] op_sel_hi:[1,0]
	v_pk_fma_f32 v[190:191], v[116:117], v[74:75], v[190:191] op_sel_hi:[0,1,1]
	v_pk_fma_f32 v[192:193], v[116:117], v[72:73], v[192:193] op_sel_hi:[0,1,1]
	v_pk_fma_f32 v[190:191], v[26:27], v[76:77], v[190:191] op_sel:[0,1,0]
	v_pk_fma_f32 v[76:77], v[24:25], v[76:77], v[192:193] op_sel:[0,1,0]
	v_pk_fma_f32 v[190:191], v[22:23], v[78:79], v[190:191] op_sel_hi:[1,0,1]
	v_pk_fma_f32 v[76:77], v[20:21], v[78:79], v[76:77] op_sel_hi:[1,0,1]
	v_mov_b32_e32 v78, v79
	v_pk_fma_f32 v[190:191], v[18:19], v[78:79], v[190:191] op_sel_hi:[1,0,1]
	v_pk_fma_f32 v[76:77], v[16:17], v[78:79], v[76:77] op_sel_hi:[1,0,1]
	s_waitcnt lgkmcnt(0)
	v_pk_fma_f32 v[78:79], v[14:15], v[88:89], v[190:191] op_sel_hi:[1,0,1]
	v_pk_fma_f32 v[76:77], v[12:13], v[88:89], v[76:77] op_sel_hi:[1,0,1]
	v_pk_fma_f32 v[78:79], v[10:11], v[88:89], v[78:79] op_sel:[0,1,0]
	v_pk_fma_f32 v[76:77], v[8:9], v[88:89], v[76:77] op_sel:[0,1,0]
	v_pk_fma_f32 v[78:79], v[6:7], v[90:91], v[78:79] op_sel_hi:[1,0,1]
	v_pk_fma_f32 v[76:77], v[4:5], v[90:91], v[76:77] op_sel_hi:[1,0,1]
	v_mov_b32_e32 v88, v91
	v_pk_fma_f32 v[78:79], v[2:3], v[88:89], v[78:79] op_sel_hi:[1,0,1]
	v_pk_fma_f32 v[76:77], v[0:1], v[88:89], v[76:77] op_sel_hi:[1,0,1]
	v_add_co_u32_e64 v88, s[16:17], s70, v118
	v_pk_fma_f32 v[90:91], v[74:75], v[80:81], v[92:93] op_sel_hi:[1,0,1]
	s_nop 0
	v_addc_co_u32_e64 v89, s[16:17], 0, v119, s[16:17]
	global_store_dwordx4 v[88:89], v[76:79], off nt
	v_pk_fma_f32 v[92:93], v[72:73], v[80:81], v[94:95] op_sel_hi:[1,0,1]
	v_pk_fma_f32 v[94:95], v[74:75], v[80:81], v[166:167] op_sel:[0,1,0]
	v_mov_b32_e32 v76, v83
	v_mov_b32_e32 v78, v87
	v_pk_fma_f32 v[166:167], v[72:73], v[80:81], v[168:169] op_sel:[0,1,0]
	v_pk_fma_f32 v[168:169], v[74:75], v[82:83], v[170:171] op_sel_hi:[1,0,1]
	v_pk_fma_f32 v[170:171], v[72:73], v[82:83], v[172:173] op_sel_hi:[1,0,1]
	v_pk_fma_f32 v[172:173], v[74:75], v[76:77], v[174:175] op_sel_hi:[1,0,1]
	v_pk_fma_f32 v[174:175], v[72:73], v[76:77], v[176:177] op_sel_hi:[1,0,1]
	v_pk_fma_f32 v[176:177], v[74:75], v[84:85], v[178:179] op_sel_hi:[1,0,1]
	v_pk_fma_f32 v[178:179], v[72:73], v[84:85], v[180:181] op_sel_hi:[1,0,1]
	v_pk_fma_f32 v[180:181], v[74:75], v[84:85], v[182:183] op_sel:[0,1,0]
	v_pk_fma_f32 v[182:183], v[74:75], v[86:87], v[184:185] op_sel_hi:[1,0,1]
	v_pk_fma_f32 v[164:165], v[74:75], v[78:79], v[164:165] op_sel_hi:[1,0,1]
	ds_read_b128 v[74:77], v136 offset:4096
	v_pk_fma_f32 v[162:163], v[72:73], v[84:85], v[162:163] op_sel:[0,1,0]
	v_pk_fma_f32 v[184:185], v[72:73], v[86:87], v[186:187] op_sel_hi:[1,0,1]
	v_pk_fma_f32 v[186:187], v[72:73], v[78:79], v[188:189] op_sel_hi:[1,0,1]
	ds_read_b128 v[78:81], v136
	ds_read_b128 v[82:85], v136 offset:16
	ds_read_b128 v[86:89], v136 offset:4112
	s_waitcnt lgkmcnt(3)
	v_pk_mul_f32 v[72:73], v[34:35], v[74:75] op_sel_hi:[1,0]
	v_pk_mul_f32 v[188:189], v[32:33], v[74:75] op_sel_hi:[1,0]
	s_waitcnt vmcnt(15)
	v_pk_fma_f32 v[72:73], v[116:117], v[70:71], v[72:73] op_sel_hi:[0,1,1]
	v_pk_fma_f32 v[188:189], v[116:117], v[68:69], v[188:189] op_sel_hi:[0,1,1]
	v_pk_fma_f32 v[72:73], v[26:27], v[74:75], v[72:73] op_sel:[0,1,0]
	v_pk_fma_f32 v[74:75], v[24:25], v[74:75], v[188:189] op_sel:[0,1,0]
	v_pk_fma_f32 v[72:73], v[22:23], v[76:77], v[72:73] op_sel_hi:[1,0,1]
	v_pk_fma_f32 v[74:75], v[20:21], v[76:77], v[74:75] op_sel_hi:[1,0,1]
	v_mov_b32_e32 v76, v77
	v_pk_fma_f32 v[72:73], v[18:19], v[76:77], v[72:73] op_sel_hi:[1,0,1]
	v_pk_fma_f32 v[74:75], v[16:17], v[76:77], v[74:75] op_sel_hi:[1,0,1]
	s_waitcnt lgkmcnt(0)
	v_pk_fma_f32 v[72:73], v[14:15], v[86:87], v[72:73] op_sel_hi:[1,0,1]
	v_pk_fma_f32 v[74:75], v[12:13], v[86:87], v[74:75] op_sel_hi:[1,0,1]
	v_pk_fma_f32 v[72:73], v[10:11], v[86:87], v[72:73] op_sel:[0,1,0]
	v_pk_fma_f32 v[74:75], v[8:9], v[86:87], v[74:75] op_sel:[0,1,0]
	v_pk_fma_f32 v[72:73], v[6:7], v[88:89], v[72:73] op_sel_hi:[1,0,1]
	v_pk_fma_f32 v[76:77], v[4:5], v[88:89], v[74:75] op_sel_hi:[1,0,1]
	v_mov_b32_e32 v86, v89
	v_pk_fma_f32 v[74:75], v[2:3], v[86:87], v[72:73] op_sel_hi:[1,0,1]
	v_pk_fma_f32 v[72:73], v[0:1], v[86:87], v[76:77] op_sel_hi:[1,0,1]
	v_add_co_u32_e64 v76, s[16:17], s71, v118
	v_pk_fma_f32 v[86:87], v[70:71], v[78:79], v[90:91] op_sel_hi:[1,0,1]
	s_nop 0
	v_addc_co_u32_e64 v77, s[16:17], 0, v119, s[16:17]
	global_store_dwordx4 v[76:77], v[72:75], off nt
	v_pk_fma_f32 v[88:89], v[68:69], v[78:79], v[92:93] op_sel_hi:[1,0,1]
	v_pk_fma_f32 v[90:91], v[70:71], v[78:79], v[94:95] op_sel:[0,1,0]
	v_mov_b32_e32 v72, v81
	v_mov_b32_e32 v74, v85
	v_pk_fma_f32 v[92:93], v[68:69], v[78:79], v[166:167] op_sel:[0,1,0]
	v_pk_fma_f32 v[94:95], v[70:71], v[80:81], v[168:169] op_sel_hi:[1,0,1]
	v_pk_fma_f32 v[166:167], v[68:69], v[80:81], v[170:171] op_sel_hi:[1,0,1]
	v_pk_fma_f32 v[168:169], v[70:71], v[72:73], v[172:173] op_sel_hi:[1,0,1]
	v_pk_fma_f32 v[170:171], v[68:69], v[72:73], v[174:175] op_sel_hi:[1,0,1]
	v_pk_fma_f32 v[172:173], v[70:71], v[82:83], v[176:177] op_sel_hi:[1,0,1]
	v_pk_fma_f32 v[174:175], v[68:69], v[82:83], v[178:179] op_sel_hi:[1,0,1]
	v_pk_fma_f32 v[176:177], v[70:71], v[82:83], v[180:181] op_sel:[0,1,0]
	v_pk_fma_f32 v[178:179], v[70:71], v[84:85], v[182:183] op_sel_hi:[1,0,1]
	v_pk_fma_f32 v[164:165], v[70:71], v[74:75], v[164:165] op_sel_hi:[1,0,1]
	ds_read_b128 v[70:73], v137 offset:4096
	v_pk_fma_f32 v[162:163], v[68:69], v[82:83], v[162:163] op_sel:[0,1,0]
	v_pk_fma_f32 v[180:181], v[68:69], v[84:85], v[184:185] op_sel_hi:[1,0,1]
	v_pk_fma_f32 v[182:183], v[68:69], v[74:75], v[186:187] op_sel_hi:[1,0,1]
	ds_read_b128 v[74:77], v137
	ds_read_b128 v[78:81], v137 offset:16
	ds_read_b128 v[82:85], v137 offset:4112
	s_waitcnt lgkmcnt(3)
	v_pk_mul_f32 v[68:69], v[34:35], v[70:71] op_sel_hi:[1,0]
	v_pk_mul_f32 v[184:185], v[32:33], v[70:71] op_sel_hi:[1,0]
	s_waitcnt vmcnt(15)
	v_pk_fma_f32 v[68:69], v[116:117], v[66:67], v[68:69] op_sel_hi:[0,1,1]
	v_pk_fma_f32 v[184:185], v[116:117], v[64:65], v[184:185] op_sel_hi:[0,1,1]
	v_pk_fma_f32 v[68:69], v[26:27], v[70:71], v[68:69] op_sel:[0,1,0]
	v_pk_fma_f32 v[70:71], v[24:25], v[70:71], v[184:185] op_sel:[0,1,0]
	v_pk_fma_f32 v[68:69], v[22:23], v[72:73], v[68:69] op_sel_hi:[1,0,1]
	v_pk_fma_f32 v[70:71], v[20:21], v[72:73], v[70:71] op_sel_hi:[1,0,1]
	v_mov_b32_e32 v72, v73
	v_pk_fma_f32 v[68:69], v[18:19], v[72:73], v[68:69] op_sel_hi:[1,0,1]
	v_pk_fma_f32 v[70:71], v[16:17], v[72:73], v[70:71] op_sel_hi:[1,0,1]
	s_waitcnt lgkmcnt(0)
	v_pk_fma_f32 v[68:69], v[14:15], v[82:83], v[68:69] op_sel_hi:[1,0,1]
	v_pk_fma_f32 v[70:71], v[12:13], v[82:83], v[70:71] op_sel_hi:[1,0,1]
	v_pk_fma_f32 v[68:69], v[10:11], v[82:83], v[68:69] op_sel:[0,1,0]
	v_pk_fma_f32 v[70:71], v[8:9], v[82:83], v[70:71] op_sel:[0,1,0]
	v_pk_fma_f32 v[68:69], v[6:7], v[84:85], v[68:69] op_sel_hi:[1,0,1]
	v_pk_fma_f32 v[72:73], v[4:5], v[84:85], v[70:71] op_sel_hi:[1,0,1]
	v_mov_b32_e32 v82, v85
	v_pk_fma_f32 v[70:71], v[2:3], v[82:83], v[68:69] op_sel_hi:[1,0,1]
	v_pk_fma_f32 v[68:69], v[0:1], v[82:83], v[72:73] op_sel_hi:[1,0,1]
	v_add_co_u32_e64 v72, s[16:17], s72, v118
	v_pk_fma_f32 v[82:83], v[66:67], v[74:75], v[86:87] op_sel_hi:[1,0,1]
	s_nop 0
	v_addc_co_u32_e64 v73, s[16:17], 0, v119, s[16:17]
	global_store_dwordx4 v[72:73], v[68:71], off nt
	v_pk_fma_f32 v[84:85], v[64:65], v[74:75], v[88:89] op_sel_hi:[1,0,1]
	v_pk_fma_f32 v[86:87], v[66:67], v[74:75], v[90:91] op_sel:[0,1,0]
	v_mov_b32_e32 v68, v77
	v_mov_b32_e32 v70, v81
	v_pk_fma_f32 v[88:89], v[64:65], v[74:75], v[92:93] op_sel:[0,1,0]
	v_pk_fma_f32 v[90:91], v[66:67], v[76:77], v[94:95] op_sel_hi:[1,0,1]
	v_pk_fma_f32 v[92:93], v[64:65], v[76:77], v[166:167] op_sel_hi:[1,0,1]
	v_pk_fma_f32 v[94:95], v[66:67], v[68:69], v[168:169] op_sel_hi:[1,0,1]
	v_pk_fma_f32 v[166:167], v[64:65], v[68:69], v[170:171] op_sel_hi:[1,0,1]
	v_pk_fma_f32 v[168:169], v[66:67], v[78:79], v[172:173] op_sel_hi:[1,0,1]
	v_pk_fma_f32 v[170:171], v[64:65], v[78:79], v[174:175] op_sel_hi:[1,0,1]
	v_pk_fma_f32 v[172:173], v[66:67], v[78:79], v[176:177] op_sel:[0,1,0]
	v_pk_fma_f32 v[174:175], v[66:67], v[80:81], v[178:179] op_sel_hi:[1,0,1]
	v_pk_fma_f32 v[164:165], v[66:67], v[70:71], v[164:165] op_sel_hi:[1,0,1]
	ds_read_b128 v[66:69], v138 offset:4096
	v_pk_fma_f32 v[162:163], v[64:65], v[78:79], v[162:163] op_sel:[0,1,0]
	v_pk_fma_f32 v[176:177], v[64:65], v[80:81], v[180:181] op_sel_hi:[1,0,1]
	v_pk_fma_f32 v[178:179], v[64:65], v[70:71], v[182:183] op_sel_hi:[1,0,1]
	ds_read_b128 v[70:73], v138
	ds_read_b128 v[74:77], v138 offset:16
	ds_read_b128 v[78:81], v138 offset:4112
	s_waitcnt lgkmcnt(3)
	v_pk_mul_f32 v[64:65], v[34:35], v[66:67] op_sel_hi:[1,0]
	v_pk_mul_f32 v[180:181], v[32:33], v[66:67] op_sel_hi:[1,0]
	s_waitcnt vmcnt(15)
	v_pk_fma_f32 v[64:65], v[116:117], v[62:63], v[64:65] op_sel_hi:[0,1,1]
	v_pk_fma_f32 v[180:181], v[116:117], v[60:61], v[180:181] op_sel_hi:[0,1,1]
	v_pk_fma_f32 v[64:65], v[26:27], v[66:67], v[64:65] op_sel:[0,1,0]
	v_pk_fma_f32 v[66:67], v[24:25], v[66:67], v[180:181] op_sel:[0,1,0]
	v_pk_fma_f32 v[64:65], v[22:23], v[68:69], v[64:65] op_sel_hi:[1,0,1]
	v_pk_fma_f32 v[66:67], v[20:21], v[68:69], v[66:67] op_sel_hi:[1,0,1]
	v_mov_b32_e32 v68, v69
	v_pk_fma_f32 v[64:65], v[18:19], v[68:69], v[64:65] op_sel_hi:[1,0,1]
	v_pk_fma_f32 v[66:67], v[16:17], v[68:69], v[66:67] op_sel_hi:[1,0,1]
	s_waitcnt lgkmcnt(0)
	v_pk_fma_f32 v[64:65], v[14:15], v[78:79], v[64:65] op_sel_hi:[1,0,1]
	v_pk_fma_f32 v[66:67], v[12:13], v[78:79], v[66:67] op_sel_hi:[1,0,1]
	v_pk_fma_f32 v[64:65], v[10:11], v[78:79], v[64:65] op_sel:[0,1,0]
	v_pk_fma_f32 v[66:67], v[8:9], v[78:79], v[66:67] op_sel:[0,1,0]
	v_pk_fma_f32 v[64:65], v[6:7], v[80:81], v[64:65] op_sel_hi:[1,0,1]
	v_pk_fma_f32 v[68:69], v[4:5], v[80:81], v[66:67] op_sel_hi:[1,0,1]
	v_mov_b32_e32 v78, v81
	v_pk_fma_f32 v[66:67], v[2:3], v[78:79], v[64:65] op_sel_hi:[1,0,1]
	v_pk_fma_f32 v[64:65], v[0:1], v[78:79], v[68:69] op_sel_hi:[1,0,1]
	v_add_co_u32_e64 v68, s[16:17], s73, v118
	v_pk_fma_f32 v[78:79], v[62:63], v[70:71], v[82:83] op_sel_hi:[1,0,1]
	s_nop 0
	v_addc_co_u32_e64 v69, s[16:17], 0, v119, s[16:17]
	global_store_dwordx4 v[68:69], v[64:67], off nt
	v_pk_fma_f32 v[80:81], v[60:61], v[70:71], v[84:85] op_sel_hi:[1,0,1]
	v_pk_fma_f32 v[82:83], v[62:63], v[70:71], v[86:87] op_sel:[0,1,0]
	v_mov_b32_e32 v64, v73
	v_mov_b32_e32 v66, v77
	v_pk_fma_f32 v[84:85], v[60:61], v[70:71], v[88:89] op_sel:[0,1,0]
	v_pk_fma_f32 v[86:87], v[62:63], v[72:73], v[90:91] op_sel_hi:[1,0,1]
	v_pk_fma_f32 v[88:89], v[60:61], v[72:73], v[92:93] op_sel_hi:[1,0,1]
	v_pk_fma_f32 v[90:91], v[62:63], v[64:65], v[94:95] op_sel_hi:[1,0,1]
	v_pk_fma_f32 v[92:93], v[60:61], v[64:65], v[166:167] op_sel_hi:[1,0,1]
	v_pk_fma_f32 v[94:95], v[62:63], v[74:75], v[168:169] op_sel_hi:[1,0,1]
	v_pk_fma_f32 v[166:167], v[60:61], v[74:75], v[170:171] op_sel_hi:[1,0,1]
	v_pk_fma_f32 v[168:169], v[62:63], v[74:75], v[172:173] op_sel:[0,1,0]
	v_pk_fma_f32 v[170:171], v[62:63], v[76:77], v[174:175] op_sel_hi:[1,0,1]
	v_pk_fma_f32 v[164:165], v[62:63], v[66:67], v[164:165] op_sel_hi:[1,0,1]
	ds_read_b128 v[62:65], v139 offset:4096
	v_pk_fma_f32 v[162:163], v[60:61], v[74:75], v[162:163] op_sel:[0,1,0]
	v_pk_fma_f32 v[172:173], v[60:61], v[76:77], v[176:177] op_sel_hi:[1,0,1]
	v_pk_fma_f32 v[174:175], v[60:61], v[66:67], v[178:179] op_sel_hi:[1,0,1]
	ds_read_b128 v[66:69], v139
	ds_read_b128 v[70:73], v139 offset:16
	ds_read_b128 v[74:77], v139 offset:4112
	s_waitcnt lgkmcnt(3)
	v_pk_mul_f32 v[60:61], v[34:35], v[62:63] op_sel_hi:[1,0]
	v_pk_mul_f32 v[176:177], v[32:33], v[62:63] op_sel_hi:[1,0]
	s_waitcnt vmcnt(15)
	v_pk_fma_f32 v[60:61], v[116:117], v[58:59], v[60:61] op_sel_hi:[0,1,1]
	v_pk_fma_f32 v[176:177], v[116:117], v[56:57], v[176:177] op_sel_hi:[0,1,1]
	v_pk_fma_f32 v[60:61], v[26:27], v[62:63], v[60:61] op_sel:[0,1,0]
	v_pk_fma_f32 v[62:63], v[24:25], v[62:63], v[176:177] op_sel:[0,1,0]
	v_pk_fma_f32 v[60:61], v[22:23], v[64:65], v[60:61] op_sel_hi:[1,0,1]
	v_pk_fma_f32 v[62:63], v[20:21], v[64:65], v[62:63] op_sel_hi:[1,0,1]
	v_mov_b32_e32 v64, v65
	v_pk_fma_f32 v[60:61], v[18:19], v[64:65], v[60:61] op_sel_hi:[1,0,1]
	v_pk_fma_f32 v[62:63], v[16:17], v[64:65], v[62:63] op_sel_hi:[1,0,1]
	s_waitcnt lgkmcnt(0)
	v_pk_fma_f32 v[60:61], v[14:15], v[74:75], v[60:61] op_sel_hi:[1,0,1]
	v_pk_fma_f32 v[62:63], v[12:13], v[74:75], v[62:63] op_sel_hi:[1,0,1]
	v_pk_fma_f32 v[60:61], v[10:11], v[74:75], v[60:61] op_sel:[0,1,0]
	v_pk_fma_f32 v[62:63], v[8:9], v[74:75], v[62:63] op_sel:[0,1,0]
	v_pk_fma_f32 v[60:61], v[6:7], v[76:77], v[60:61] op_sel_hi:[1,0,1]
	v_pk_fma_f32 v[64:65], v[4:5], v[76:77], v[62:63] op_sel_hi:[1,0,1]
	v_mov_b32_e32 v74, v77
	v_pk_fma_f32 v[62:63], v[2:3], v[74:75], v[60:61] op_sel_hi:[1,0,1]
	v_pk_fma_f32 v[60:61], v[0:1], v[74:75], v[64:65] op_sel_hi:[1,0,1]
	v_add_co_u32_e64 v64, s[16:17], s74, v118
	v_pk_fma_f32 v[74:75], v[58:59], v[66:67], v[78:79] op_sel_hi:[1,0,1]
	s_nop 0
	v_addc_co_u32_e64 v65, s[16:17], 0, v119, s[16:17]
	global_store_dwordx4 v[64:65], v[60:63], off nt
	v_pk_fma_f32 v[76:77], v[56:57], v[66:67], v[80:81] op_sel_hi:[1,0,1]
	v_pk_fma_f32 v[78:79], v[58:59], v[66:67], v[82:83] op_sel:[0,1,0]
	v_mov_b32_e32 v60, v69
	v_mov_b32_e32 v62, v73
	v_pk_fma_f32 v[80:81], v[56:57], v[66:67], v[84:85] op_sel:[0,1,0]
	v_pk_fma_f32 v[82:83], v[58:59], v[68:69], v[86:87] op_sel_hi:[1,0,1]
	v_pk_fma_f32 v[84:85], v[56:57], v[68:69], v[88:89] op_sel_hi:[1,0,1]
	v_pk_fma_f32 v[86:87], v[58:59], v[60:61], v[90:91] op_sel_hi:[1,0,1]
	v_pk_fma_f32 v[88:89], v[56:57], v[60:61], v[92:93] op_sel_hi:[1,0,1]
	v_pk_fma_f32 v[90:91], v[58:59], v[70:71], v[94:95] op_sel_hi:[1,0,1]
	v_pk_fma_f32 v[92:93], v[56:57], v[70:71], v[166:167] op_sel_hi:[1,0,1]
	v_pk_fma_f32 v[94:95], v[58:59], v[70:71], v[168:169] op_sel:[0,1,0]
	v_pk_fma_f32 v[166:167], v[58:59], v[72:73], v[170:171] op_sel_hi:[1,0,1]
	v_pk_fma_f32 v[164:165], v[58:59], v[62:63], v[164:165] op_sel_hi:[1,0,1]
	ds_read_b128 v[58:61], v140 offset:4096
	v_pk_fma_f32 v[162:163], v[56:57], v[70:71], v[162:163] op_sel:[0,1,0]
	v_pk_fma_f32 v[168:169], v[56:57], v[72:73], v[172:173] op_sel_hi:[1,0,1]
	v_pk_fma_f32 v[170:171], v[56:57], v[62:63], v[174:175] op_sel_hi:[1,0,1]
	ds_read_b128 v[62:65], v140
	ds_read_b128 v[66:69], v140 offset:16
	ds_read_b128 v[70:73], v140 offset:4112
	s_waitcnt lgkmcnt(3)
	v_pk_mul_f32 v[56:57], v[34:35], v[58:59] op_sel_hi:[1,0]
	v_pk_mul_f32 v[172:173], v[32:33], v[58:59] op_sel_hi:[1,0]
	s_waitcnt vmcnt(15)
	v_pk_fma_f32 v[56:57], v[116:117], v[54:55], v[56:57] op_sel_hi:[0,1,1]
	v_pk_fma_f32 v[172:173], v[116:117], v[52:53], v[172:173] op_sel_hi:[0,1,1]
	v_pk_fma_f32 v[56:57], v[26:27], v[58:59], v[56:57] op_sel:[0,1,0]
	v_pk_fma_f32 v[58:59], v[24:25], v[58:59], v[172:173] op_sel:[0,1,0]
	v_pk_fma_f32 v[56:57], v[22:23], v[60:61], v[56:57] op_sel_hi:[1,0,1]
	v_pk_fma_f32 v[58:59], v[20:21], v[60:61], v[58:59] op_sel_hi:[1,0,1]
	v_mov_b32_e32 v60, v61
	v_pk_fma_f32 v[56:57], v[18:19], v[60:61], v[56:57] op_sel_hi:[1,0,1]
	v_pk_fma_f32 v[58:59], v[16:17], v[60:61], v[58:59] op_sel_hi:[1,0,1]
	s_waitcnt lgkmcnt(0)
	v_pk_fma_f32 v[56:57], v[14:15], v[70:71], v[56:57] op_sel_hi:[1,0,1]
	v_pk_fma_f32 v[58:59], v[12:13], v[70:71], v[58:59] op_sel_hi:[1,0,1]
	v_pk_fma_f32 v[56:57], v[10:11], v[70:71], v[56:57] op_sel:[0,1,0]
	v_pk_fma_f32 v[58:59], v[8:9], v[70:71], v[58:59] op_sel:[0,1,0]
	v_pk_fma_f32 v[56:57], v[6:7], v[72:73], v[56:57] op_sel_hi:[1,0,1]
	v_pk_fma_f32 v[60:61], v[4:5], v[72:73], v[58:59] op_sel_hi:[1,0,1]
	v_mov_b32_e32 v70, v73
	v_pk_fma_f32 v[58:59], v[2:3], v[70:71], v[56:57] op_sel_hi:[1,0,1]
	v_pk_fma_f32 v[56:57], v[0:1], v[70:71], v[60:61] op_sel_hi:[1,0,1]
	v_add_co_u32_e64 v60, s[16:17], s75, v118
	v_pk_fma_f32 v[70:71], v[54:55], v[62:63], v[74:75] op_sel_hi:[1,0,1]
	s_nop 0
	v_addc_co_u32_e64 v61, s[16:17], 0, v119, s[16:17]
	global_store_dwordx4 v[60:61], v[56:59], off nt
	v_pk_fma_f32 v[72:73], v[52:53], v[62:63], v[76:77] op_sel_hi:[1,0,1]
	v_pk_fma_f32 v[74:75], v[54:55], v[62:63], v[78:79] op_sel:[0,1,0]
	v_mov_b32_e32 v56, v65
	v_mov_b32_e32 v58, v69
	v_pk_fma_f32 v[76:77], v[52:53], v[62:63], v[80:81] op_sel:[0,1,0]
	v_pk_fma_f32 v[78:79], v[54:55], v[64:65], v[82:83] op_sel_hi:[1,0,1]
	v_pk_fma_f32 v[80:81], v[52:53], v[64:65], v[84:85] op_sel_hi:[1,0,1]
	v_pk_fma_f32 v[82:83], v[54:55], v[56:57], v[86:87] op_sel_hi:[1,0,1]
	v_pk_fma_f32 v[84:85], v[52:53], v[56:57], v[88:89] op_sel_hi:[1,0,1]
	v_pk_fma_f32 v[86:87], v[54:55], v[66:67], v[90:91] op_sel_hi:[1,0,1]
	v_pk_fma_f32 v[90:91], v[54:55], v[66:67], v[94:95] op_sel:[0,1,0]
	v_pk_fma_f32 v[94:95], v[54:55], v[68:69], v[166:167] op_sel_hi:[1,0,1]
	v_pk_fma_f32 v[164:165], v[54:55], v[58:59], v[164:165] op_sel_hi:[1,0,1]
	ds_read_b128 v[54:57], v141 offset:4096
	v_pk_fma_f32 v[88:89], v[52:53], v[66:67], v[92:93] op_sel_hi:[1,0,1]
	v_pk_fma_f32 v[92:93], v[52:53], v[66:67], v[162:163] op_sel:[0,1,0]
	v_pk_fma_f32 v[162:163], v[52:53], v[68:69], v[168:169] op_sel_hi:[1,0,1]
	v_pk_fma_f32 v[166:167], v[52:53], v[58:59], v[170:171] op_sel_hi:[1,0,1]
	ds_read_b128 v[58:61], v141
	ds_read_b128 v[62:65], v141 offset:16
	ds_read_b128 v[66:69], v141 offset:4112
	s_waitcnt lgkmcnt(3)
	v_pk_mul_f32 v[52:53], v[34:35], v[54:55] op_sel_hi:[1,0]
	v_pk_mul_f32 v[168:169], v[32:33], v[54:55] op_sel_hi:[1,0]
	s_waitcnt vmcnt(15)
	v_pk_fma_f32 v[52:53], v[116:117], v[50:51], v[52:53] op_sel_hi:[0,1,1]
	v_pk_fma_f32 v[168:169], v[116:117], v[48:49], v[168:169] op_sel_hi:[0,1,1]
	v_pk_fma_f32 v[52:53], v[26:27], v[54:55], v[52:53] op_sel:[0,1,0]
	v_pk_fma_f32 v[54:55], v[24:25], v[54:55], v[168:169] op_sel:[0,1,0]
	v_pk_fma_f32 v[52:53], v[22:23], v[56:57], v[52:53] op_sel_hi:[1,0,1]
	v_pk_fma_f32 v[54:55], v[20:21], v[56:57], v[54:55] op_sel_hi:[1,0,1]
	v_mov_b32_e32 v56, v57
	v_pk_fma_f32 v[52:53], v[18:19], v[56:57], v[52:53] op_sel_hi:[1,0,1]
	v_pk_fma_f32 v[54:55], v[16:17], v[56:57], v[54:55] op_sel_hi:[1,0,1]
	s_waitcnt lgkmcnt(0)
	v_pk_fma_f32 v[52:53], v[14:15], v[66:67], v[52:53] op_sel_hi:[1,0,1]
	v_pk_fma_f32 v[54:55], v[12:13], v[66:67], v[54:55] op_sel_hi:[1,0,1]
	v_pk_fma_f32 v[52:53], v[10:11], v[66:67], v[52:53] op_sel:[0,1,0]
	v_pk_fma_f32 v[54:55], v[8:9], v[66:67], v[54:55] op_sel:[0,1,0]
	v_pk_fma_f32 v[52:53], v[6:7], v[68:69], v[52:53] op_sel_hi:[1,0,1]
	v_pk_fma_f32 v[56:57], v[4:5], v[68:69], v[54:55] op_sel_hi:[1,0,1]
	v_mov_b32_e32 v66, v69
	v_pk_fma_f32 v[54:55], v[2:3], v[66:67], v[52:53] op_sel_hi:[1,0,1]
	v_pk_fma_f32 v[52:53], v[0:1], v[66:67], v[56:57] op_sel_hi:[1,0,1]
	v_add_co_u32_e64 v56, s[16:17], s76, v118
	v_pk_fma_f32 v[66:67], v[50:51], v[58:59], v[70:71] op_sel_hi:[1,0,1]
	s_nop 0
	v_addc_co_u32_e64 v57, s[16:17], 0, v119, s[16:17]
	global_store_dwordx4 v[56:57], v[52:55], off nt
	v_pk_fma_f32 v[68:69], v[48:49], v[58:59], v[72:73] op_sel_hi:[1,0,1]
	v_pk_fma_f32 v[70:71], v[50:51], v[58:59], v[74:75] op_sel:[0,1,0]
	v_mov_b32_e32 v52, v61
	v_mov_b32_e32 v54, v65
	v_pk_fma_f32 v[72:73], v[48:49], v[58:59], v[76:77] op_sel:[0,1,0]
	v_pk_fma_f32 v[74:75], v[50:51], v[60:61], v[78:79] op_sel_hi:[1,0,1]
	v_pk_fma_f32 v[76:77], v[48:49], v[60:61], v[80:81] op_sel_hi:[1,0,1]
	v_pk_fma_f32 v[78:79], v[50:51], v[52:53], v[82:83] op_sel_hi:[1,0,1]
	v_pk_fma_f32 v[80:81], v[48:49], v[52:53], v[84:85] op_sel_hi:[1,0,1]
	v_pk_fma_f32 v[82:83], v[50:51], v[62:63], v[86:87] op_sel_hi:[1,0,1]
	v_pk_fma_f32 v[86:87], v[50:51], v[62:63], v[90:91] op_sel:[0,1,0]
	v_pk_fma_f32 v[90:91], v[50:51], v[64:65], v[94:95] op_sel_hi:[1,0,1]
	v_pk_fma_f32 v[94:95], v[50:51], v[54:55], v[164:165] op_sel_hi:[1,0,1]
	ds_read_b128 v[50:53], v142 offset:4096
	v_pk_fma_f32 v[84:85], v[48:49], v[62:63], v[88:89] op_sel_hi:[1,0,1]
	v_pk_fma_f32 v[88:89], v[48:49], v[62:63], v[92:93] op_sel:[0,1,0]
	v_pk_fma_f32 v[92:93], v[48:49], v[64:65], v[162:163] op_sel_hi:[1,0,1]
	v_pk_fma_f32 v[162:163], v[48:49], v[54:55], v[166:167] op_sel_hi:[1,0,1]
	ds_read_b128 v[54:57], v142
	ds_read_b128 v[58:61], v142 offset:16
	ds_read_b128 v[62:65], v142 offset:4112
	s_waitcnt lgkmcnt(3)
	v_pk_mul_f32 v[48:49], v[34:35], v[50:51] op_sel_hi:[1,0]
	v_pk_mul_f32 v[164:165], v[32:33], v[50:51] op_sel_hi:[1,0]
	s_waitcnt vmcnt(15)
	v_pk_fma_f32 v[48:49], v[116:117], v[46:47], v[48:49] op_sel_hi:[0,1,1]
	v_pk_fma_f32 v[164:165], v[116:117], v[44:45], v[164:165] op_sel_hi:[0,1,1]
	v_pk_fma_f32 v[48:49], v[26:27], v[50:51], v[48:49] op_sel:[0,1,0]
	v_pk_fma_f32 v[50:51], v[24:25], v[50:51], v[164:165] op_sel:[0,1,0]
	v_pk_fma_f32 v[48:49], v[22:23], v[52:53], v[48:49] op_sel_hi:[1,0,1]
	v_pk_fma_f32 v[50:51], v[20:21], v[52:53], v[50:51] op_sel_hi:[1,0,1]
	v_mov_b32_e32 v52, v53
	v_pk_fma_f32 v[48:49], v[18:19], v[52:53], v[48:49] op_sel_hi:[1,0,1]
	v_pk_fma_f32 v[50:51], v[16:17], v[52:53], v[50:51] op_sel_hi:[1,0,1]
	s_waitcnt lgkmcnt(0)
	v_pk_fma_f32 v[48:49], v[14:15], v[62:63], v[48:49] op_sel_hi:[1,0,1]
	v_pk_fma_f32 v[50:51], v[12:13], v[62:63], v[50:51] op_sel_hi:[1,0,1]
	v_pk_fma_f32 v[48:49], v[10:11], v[62:63], v[48:49] op_sel:[0,1,0]
	v_pk_fma_f32 v[50:51], v[8:9], v[62:63], v[50:51] op_sel:[0,1,0]
	v_pk_fma_f32 v[48:49], v[6:7], v[64:65], v[48:49] op_sel_hi:[1,0,1]
	v_pk_fma_f32 v[52:53], v[4:5], v[64:65], v[50:51] op_sel_hi:[1,0,1]
	v_mov_b32_e32 v62, v65
	v_pk_fma_f32 v[50:51], v[2:3], v[62:63], v[48:49] op_sel_hi:[1,0,1]
	v_pk_fma_f32 v[48:49], v[0:1], v[62:63], v[52:53] op_sel_hi:[1,0,1]
	v_add_co_u32_e64 v52, s[16:17], s77, v118
	v_pk_fma_f32 v[62:63], v[46:47], v[54:55], v[66:67] op_sel_hi:[1,0,1]
	s_nop 0
	v_addc_co_u32_e64 v53, s[16:17], 0, v119, s[16:17]
	global_store_dwordx4 v[52:53], v[48:51], off nt
	v_pk_fma_f32 v[64:65], v[44:45], v[54:55], v[68:69] op_sel_hi:[1,0,1]
	v_pk_fma_f32 v[66:67], v[46:47], v[54:55], v[70:71] op_sel:[0,1,0]
	v_mov_b32_e32 v48, v57
	v_mov_b32_e32 v50, v61
	v_pk_fma_f32 v[68:69], v[44:45], v[54:55], v[72:73] op_sel:[0,1,0]
	v_pk_fma_f32 v[70:71], v[46:47], v[56:57], v[74:75] op_sel_hi:[1,0,1]
	v_pk_fma_f32 v[72:73], v[44:45], v[56:57], v[76:77] op_sel_hi:[1,0,1]
	v_pk_fma_f32 v[74:75], v[46:47], v[48:49], v[78:79] op_sel_hi:[1,0,1]
	v_pk_fma_f32 v[76:77], v[44:45], v[48:49], v[80:81] op_sel_hi:[1,0,1]
	v_pk_fma_f32 v[78:79], v[46:47], v[58:59], v[82:83] op_sel_hi:[1,0,1]
	v_pk_fma_f32 v[82:83], v[46:47], v[58:59], v[86:87] op_sel:[0,1,0]
	v_pk_fma_f32 v[86:87], v[46:47], v[60:61], v[90:91] op_sel_hi:[1,0,1]
	v_pk_fma_f32 v[90:91], v[46:47], v[50:51], v[94:95] op_sel_hi:[1,0,1]
	ds_read_b128 v[46:49], v143 offset:4096
	v_pk_fma_f32 v[80:81], v[44:45], v[58:59], v[84:85] op_sel_hi:[1,0,1]
	v_pk_fma_f32 v[84:85], v[44:45], v[58:59], v[88:89] op_sel:[0,1,0]
	v_pk_fma_f32 v[88:89], v[44:45], v[60:61], v[92:93] op_sel_hi:[1,0,1]
	v_pk_fma_f32 v[92:93], v[44:45], v[50:51], v[162:163] op_sel_hi:[1,0,1]
	ds_read_b128 v[50:53], v143
	ds_read_b128 v[54:57], v143 offset:16
	ds_read_b128 v[58:61], v143 offset:4112
	s_waitcnt lgkmcnt(3)
	v_pk_mul_f32 v[44:45], v[34:35], v[46:47] op_sel_hi:[1,0]
	v_pk_mul_f32 v[94:95], v[32:33], v[46:47] op_sel_hi:[1,0]
	s_waitcnt vmcnt(15)
	v_pk_fma_f32 v[44:45], v[116:117], v[42:43], v[44:45] op_sel_hi:[0,1,1]
	v_pk_fma_f32 v[94:95], v[116:117], v[40:41], v[94:95] op_sel_hi:[0,1,1]
	v_pk_fma_f32 v[44:45], v[26:27], v[46:47], v[44:45] op_sel:[0,1,0]
	v_pk_fma_f32 v[46:47], v[24:25], v[46:47], v[94:95] op_sel:[0,1,0]
	v_pk_fma_f32 v[44:45], v[22:23], v[48:49], v[44:45] op_sel_hi:[1,0,1]
	v_pk_fma_f32 v[46:47], v[20:21], v[48:49], v[46:47] op_sel_hi:[1,0,1]
	v_mov_b32_e32 v48, v49
	v_pk_fma_f32 v[44:45], v[18:19], v[48:49], v[44:45] op_sel_hi:[1,0,1]
	v_pk_fma_f32 v[46:47], v[16:17], v[48:49], v[46:47] op_sel_hi:[1,0,1]
	s_waitcnt lgkmcnt(0)
	v_pk_fma_f32 v[44:45], v[14:15], v[58:59], v[44:45] op_sel_hi:[1,0,1]
	v_pk_fma_f32 v[46:47], v[12:13], v[58:59], v[46:47] op_sel_hi:[1,0,1]
	v_pk_fma_f32 v[44:45], v[10:11], v[58:59], v[44:45] op_sel:[0,1,0]
	v_pk_fma_f32 v[46:47], v[8:9], v[58:59], v[46:47] op_sel:[0,1,0]
	v_pk_fma_f32 v[44:45], v[6:7], v[60:61], v[44:45] op_sel_hi:[1,0,1]
	v_pk_fma_f32 v[48:49], v[4:5], v[60:61], v[46:47] op_sel_hi:[1,0,1]
	v_mov_b32_e32 v58, v61
	v_pk_fma_f32 v[46:47], v[2:3], v[58:59], v[44:45] op_sel_hi:[1,0,1]
	v_pk_fma_f32 v[44:45], v[0:1], v[58:59], v[48:49] op_sel_hi:[1,0,1]
	v_add_co_u32_e64 v48, s[16:17], s78, v118
	v_pk_fma_f32 v[58:59], v[42:43], v[50:51], v[62:63] op_sel_hi:[1,0,1]
	s_nop 0
	v_addc_co_u32_e64 v49, s[16:17], 0, v119, s[16:17]
	global_store_dwordx4 v[48:49], v[44:47], off nt
	v_pk_fma_f32 v[60:61], v[40:41], v[50:51], v[64:65] op_sel_hi:[1,0,1]
	v_pk_fma_f32 v[62:63], v[42:43], v[50:51], v[66:67] op_sel:[0,1,0]
	v_mov_b32_e32 v44, v53
	v_mov_b32_e32 v46, v57
	v_pk_fma_f32 v[64:65], v[40:41], v[50:51], v[68:69] op_sel:[0,1,0]
	v_pk_fma_f32 v[66:67], v[42:43], v[52:53], v[70:71] op_sel_hi:[1,0,1]
	v_pk_fma_f32 v[68:69], v[40:41], v[52:53], v[72:73] op_sel_hi:[1,0,1]
	v_pk_fma_f32 v[70:71], v[42:43], v[44:45], v[74:75] op_sel_hi:[1,0,1]
	v_pk_fma_f32 v[72:73], v[40:41], v[44:45], v[76:77] op_sel_hi:[1,0,1]
	v_pk_fma_f32 v[74:75], v[42:43], v[54:55], v[78:79] op_sel_hi:[1,0,1]
	v_pk_fma_f32 v[78:79], v[42:43], v[54:55], v[82:83] op_sel:[0,1,0]
	v_pk_fma_f32 v[82:83], v[42:43], v[56:57], v[86:87] op_sel_hi:[1,0,1]
	v_pk_fma_f32 v[86:87], v[42:43], v[46:47], v[90:91] op_sel_hi:[1,0,1]
	ds_read_b128 v[42:45], v144 offset:4096
	v_pk_fma_f32 v[76:77], v[40:41], v[54:55], v[80:81] op_sel_hi:[1,0,1]
	v_pk_fma_f32 v[80:81], v[40:41], v[54:55], v[84:85] op_sel:[0,1,0]
	v_pk_fma_f32 v[84:85], v[40:41], v[56:57], v[88:89] op_sel_hi:[1,0,1]
	v_pk_fma_f32 v[88:89], v[40:41], v[46:47], v[92:93] op_sel_hi:[1,0,1]
	ds_read_b128 v[46:49], v144
	ds_read_b128 v[50:53], v144 offset:16
	ds_read_b128 v[54:57], v144 offset:4112
	s_waitcnt lgkmcnt(3)
	v_pk_mul_f32 v[40:41], v[34:35], v[42:43] op_sel_hi:[1,0]
	v_pk_mul_f32 v[90:91], v[32:33], v[42:43] op_sel_hi:[1,0]
	s_waitcnt vmcnt(15)
	v_pk_fma_f32 v[40:41], v[116:117], v[38:39], v[40:41] op_sel_hi:[0,1,1]
	v_pk_fma_f32 v[90:91], v[116:117], v[36:37], v[90:91] op_sel_hi:[0,1,1]
	v_pk_fma_f32 v[40:41], v[26:27], v[42:43], v[40:41] op_sel:[0,1,0]
	v_pk_fma_f32 v[42:43], v[24:25], v[42:43], v[90:91] op_sel:[0,1,0]
	v_pk_fma_f32 v[40:41], v[22:23], v[44:45], v[40:41] op_sel_hi:[1,0,1]
	v_pk_fma_f32 v[42:43], v[20:21], v[44:45], v[42:43] op_sel_hi:[1,0,1]
	v_mov_b32_e32 v44, v45
	v_pk_fma_f32 v[40:41], v[18:19], v[44:45], v[40:41] op_sel_hi:[1,0,1]
	v_pk_fma_f32 v[42:43], v[16:17], v[44:45], v[42:43] op_sel_hi:[1,0,1]
	s_waitcnt lgkmcnt(0)
	v_pk_fma_f32 v[40:41], v[14:15], v[54:55], v[40:41] op_sel_hi:[1,0,1]
	v_pk_fma_f32 v[42:43], v[12:13], v[54:55], v[42:43] op_sel_hi:[1,0,1]
	v_pk_fma_f32 v[40:41], v[10:11], v[54:55], v[40:41] op_sel:[0,1,0]
	v_pk_fma_f32 v[42:43], v[8:9], v[54:55], v[42:43] op_sel:[0,1,0]
	v_pk_fma_f32 v[40:41], v[6:7], v[56:57], v[40:41] op_sel_hi:[1,0,1]
	v_pk_fma_f32 v[44:45], v[4:5], v[56:57], v[42:43] op_sel_hi:[1,0,1]
	v_mov_b32_e32 v54, v57
	v_pk_fma_f32 v[42:43], v[2:3], v[54:55], v[40:41] op_sel_hi:[1,0,1]
	v_pk_fma_f32 v[40:41], v[0:1], v[54:55], v[44:45] op_sel_hi:[1,0,1]
	v_add_co_u32_e64 v44, s[16:17], s79, v118
	v_pk_fma_f32 v[54:55], v[38:39], v[46:47], v[58:59] op_sel_hi:[1,0,1]
	s_nop 0
	v_addc_co_u32_e64 v45, s[16:17], 0, v119, s[16:17]
	global_store_dwordx4 v[44:45], v[40:43], off nt
	v_pk_fma_f32 v[56:57], v[36:37], v[46:47], v[60:61] op_sel_hi:[1,0,1]
	v_pk_fma_f32 v[58:59], v[38:39], v[46:47], v[62:63] op_sel:[0,1,0]
	v_mov_b32_e32 v40, v49
	v_mov_b32_e32 v42, v53
	v_pk_fma_f32 v[60:61], v[36:37], v[46:47], v[64:65] op_sel:[0,1,0]
	v_pk_fma_f32 v[62:63], v[38:39], v[48:49], v[66:67] op_sel_hi:[1,0,1]
	v_pk_fma_f32 v[64:65], v[36:37], v[48:49], v[68:69] op_sel_hi:[1,0,1]
	v_pk_fma_f32 v[66:67], v[38:39], v[40:41], v[70:71] op_sel_hi:[1,0,1]
	v_pk_fma_f32 v[68:69], v[36:37], v[40:41], v[72:73] op_sel_hi:[1,0,1]
	v_pk_fma_f32 v[70:71], v[38:39], v[50:51], v[74:75] op_sel_hi:[1,0,1]
	v_pk_fma_f32 v[74:75], v[38:39], v[50:51], v[78:79] op_sel:[0,1,0]
	v_pk_fma_f32 v[78:79], v[38:39], v[52:53], v[82:83] op_sel_hi:[1,0,1]
	v_pk_fma_f32 v[82:83], v[38:39], v[42:43], v[86:87] op_sel_hi:[1,0,1]
	ds_read_b128 v[38:41], v145 offset:4096
	v_pk_fma_f32 v[72:73], v[36:37], v[50:51], v[76:77] op_sel_hi:[1,0,1]
	v_pk_fma_f32 v[76:77], v[36:37], v[50:51], v[80:81] op_sel:[0,1,0]
	v_pk_fma_f32 v[80:81], v[36:37], v[52:53], v[84:85] op_sel_hi:[1,0,1]
	v_pk_fma_f32 v[84:85], v[36:37], v[42:43], v[88:89] op_sel_hi:[1,0,1]
	ds_read_b128 v[42:45], v145
	ds_read_b128 v[46:49], v145 offset:16
	ds_read_b128 v[50:53], v145 offset:4112
	s_waitcnt lgkmcnt(3)
	v_pk_mul_f32 v[36:37], v[34:35], v[38:39] op_sel_hi:[1,0]
	v_pk_mul_f32 v[86:87], v[32:33], v[38:39] op_sel_hi:[1,0]
	s_waitcnt vmcnt(15)
	v_pk_fma_f32 v[36:37], v[116:117], v[30:31], v[36:37] op_sel_hi:[0,1,1]
	v_pk_fma_f32 v[86:87], v[116:117], v[28:29], v[86:87] op_sel_hi:[0,1,1]
	v_pk_fma_f32 v[36:37], v[26:27], v[38:39], v[36:37] op_sel:[0,1,0]
	v_pk_fma_f32 v[38:39], v[24:25], v[38:39], v[86:87] op_sel:[0,1,0]
	v_pk_fma_f32 v[36:37], v[22:23], v[40:41], v[36:37] op_sel_hi:[1,0,1]
	v_pk_fma_f32 v[38:39], v[20:21], v[40:41], v[38:39] op_sel_hi:[1,0,1]
	v_mov_b32_e32 v40, v41
	v_pk_fma_f32 v[36:37], v[18:19], v[40:41], v[36:37] op_sel_hi:[1,0,1]
	v_pk_fma_f32 v[38:39], v[16:17], v[40:41], v[38:39] op_sel_hi:[1,0,1]
	s_waitcnt lgkmcnt(0)
	v_pk_fma_f32 v[36:37], v[14:15], v[50:51], v[36:37] op_sel_hi:[1,0,1]
	v_pk_fma_f32 v[38:39], v[12:13], v[50:51], v[38:39] op_sel_hi:[1,0,1]
	v_pk_fma_f32 v[36:37], v[10:11], v[50:51], v[36:37] op_sel:[0,1,0]
	v_pk_fma_f32 v[38:39], v[8:9], v[50:51], v[38:39] op_sel:[0,1,0]
	v_pk_fma_f32 v[36:37], v[6:7], v[52:53], v[36:37] op_sel_hi:[1,0,1]
	v_pk_fma_f32 v[40:41], v[4:5], v[52:53], v[38:39] op_sel_hi:[1,0,1]
	v_mov_b32_e32 v50, v53
	v_pk_fma_f32 v[38:39], v[2:3], v[50:51], v[36:37] op_sel_hi:[1,0,1]
	v_pk_fma_f32 v[36:37], v[0:1], v[50:51], v[40:41] op_sel_hi:[1,0,1]
	v_add_co_u32_e64 v40, s[16:17], s80, v118
	v_pk_fma_f32 v[52:53], v[30:31], v[42:43], v[58:59] op_sel:[0,1,0]
	s_nop 0
	v_addc_co_u32_e64 v41, s[16:17], 0, v119, s[16:17]
	global_store_dwordx4 v[40:41], v[36:39], off nt
	v_pk_fma_f32 v[50:51], v[28:29], v[42:43], v[60:61] op_sel:[0,1,0]
	v_pk_fma_f32 v[40:41], v[28:29], v[44:45], v[64:65] op_sel_hi:[1,0,1]
	v_pk_fma_f32 v[38:39], v[30:31], v[42:43], v[54:55] op_sel_hi:[1,0,1]
	v_pk_fma_f32 v[36:37], v[28:29], v[42:43], v[56:57] op_sel_hi:[1,0,1]
	v_pk_fma_f32 v[42:43], v[30:31], v[44:45], v[62:63] op_sel_hi:[1,0,1]
	v_mov_b32_e32 v44, v45
	v_pk_fma_f32 v[56:57], v[30:31], v[44:45], v[66:67] op_sel_hi:[1,0,1]
	v_pk_fma_f32 v[54:55], v[28:29], v[44:45], v[68:69] op_sel_hi:[1,0,1]
	v_pk_fma_f32 v[60:61], v[30:31], v[46:47], v[70:71] op_sel_hi:[1,0,1]
	v_pk_fma_f32 v[58:59], v[28:29], v[46:47], v[72:73] op_sel_hi:[1,0,1]
	v_pk_fma_f32 v[64:65], v[30:31], v[46:47], v[74:75] op_sel:[0,1,0]
	v_pk_fma_f32 v[62:63], v[28:29], v[46:47], v[76:77] op_sel:[0,1,0]
	v_pk_fma_f32 v[46:47], v[30:31], v[48:49], v[78:79] op_sel_hi:[1,0,1]
	v_pk_fma_f32 v[44:45], v[28:29], v[48:49], v[80:81] op_sel_hi:[1,0,1]
	v_mov_b32_e32 v48, v49
	v_pk_fma_f32 v[28:29], v[28:29], v[48:49], v[84:85] op_sel_hi:[1,0,1]
	v_pk_fma_f32 v[30:31], v[30:31], v[48:49], v[82:83] op_sel_hi:[1,0,1]
	ds_write_b128 v146, v[36:39] offset:18432
	ds_write_b128 v146, v[50:53] offset:19456
	ds_write_b128 v146, v[40:43] offset:20480
	ds_write_b128 v146, v[54:57] offset:21504
	ds_write_b128 v146, v[58:61] offset:22528
	ds_write_b128 v146, v[62:65] offset:23552
	ds_write_b128 v146, v[44:47] offset:24576
	ds_write_b128 v146, v[28:31] offset:25600
	s_waitcnt lgkmcnt(0)
	s_barrier
	ds_read2st64_b32 v[28:29], v147 offset0:64 offset1:65
	ds_read2st64_b32 v[30:31], v147 offset0:66 offset1:67
	ds_read2st64_b32 v[38:39], v147 offset0:68 offset1:69
	ds_read2st64_b32 v[42:43], v147 offset0:70 offset1:71
	v_ldexp_f32 v36, v160, s18
	s_waitcnt lgkmcnt(3)
	v_add_f32_e32 v28, 0, v28
	v_add_f32_e32 v28, v28, v29
	s_waitcnt lgkmcnt(2)
	v_add_f32_e32 v28, v28, v30
	v_add_f32_e32 v28, v28, v31
	s_waitcnt lgkmcnt(1)
	v_add_f32_e32 v37, v28, v38
	ds_read_b128 v[28:31], v148 offset:18432
	v_add_f32_e32 v37, v37, v39
	s_waitcnt lgkmcnt(1)
	v_add_f32_e32 v37, v37, v42
	ds_read_b128 v[38:41], v148 offset:26624
	v_add_f32_e32 v37, v37, v43
	ds_read_b128 v[42:45], v148 offset:34816
	s_waitcnt lgkmcnt(2)
	v_pk_add_f32 v[30:31], v[30:31], 0 op_sel_hi:[1,0]
	v_pk_add_f32 v[46:47], v[28:29], 0 op_sel_hi:[1,0]
	s_waitcnt lgkmcnt(1)
	v_pk_add_f32 v[40:41], v[30:31], v[40:41]
	ds_read_b128 v[28:31], v148 offset:43008
	v_pk_add_f32 v[46:47], v[46:47], v[38:39]
	s_waitcnt lgkmcnt(1)
	v_pk_add_f32 v[44:45], v[40:41], v[44:45]
	ds_read_b128 v[38:41], v148 offset:51200
	v_pk_add_f32 v[42:43], v[46:47], v[42:43]
	s_waitcnt lgkmcnt(1)
	v_pk_add_f32 v[44:45], v[44:45], v[30:31]
	v_pk_add_f32 v[46:47], v[42:43], v[28:29]
	ds_read_b128 v[28:31], v148 offset:59392
	s_waitcnt lgkmcnt(1)
	v_pk_add_f32 v[48:49], v[44:45], v[40:41]
	ds_read_b128 v[40:43], v149 offset:49152
	v_pk_add_f32 v[38:39], v[46:47], v[38:39]
	ds_read_b128 v[44:47], v149 offset:57344
	s_waitcnt lgkmcnt(2)
	v_pk_add_f32 v[30:31], v[48:49], v[30:31]
	v_pk_add_f32 v[28:29], v[38:39], v[28:29]
	s_waitcnt lgkmcnt(1)
	v_pk_add_f32 v[30:31], v[30:31], v[42:43]
	v_pk_add_f32 v[28:29], v[28:29], v[40:41]
	s_waitcnt lgkmcnt(0)
	v_pk_add_f32 v[30:31], v[30:31], v[46:47]
	v_pk_add_f32 v[38:39], v[28:29], v[44:45]
	v_mul_f32_e32 v40, v36, v37
	v_pk_fma_f32 v[28:29], v[34:35], v[40:41], v[30:31] op_sel_hi:[1,0,1]
	v_pk_fma_f32 v[30:31], v[32:33], v[40:41], v[38:39] op_sel_hi:[1,0,1]
	s_and_saveexec_b64 s[16:17], vcc
	s_cbranch_execnz .LBB0_1024
	s_or_b64 exec, exec, s[16:17]
	s_and_saveexec_b64 s[16:17], s[4:5]
	s_cbranch_execnz .LBB0_1025

.LBB0_1033:
	v_bfe_u32 v0, v7, 6, 7
	v_lshrrev_b32_e32 v8, 1, v7
	v_and_or_b32 v0, v8, s11, v0
	v_mul_u32_u24_e32 v0, 0x2e00, v0
	v_cmp_gt_u32_e32 vcc, s12, v7
	v_lshlrev_b32_e32 v0, 1, v0
	v_and_b32_e32 v12, 0xfc, v2
	v_lshl_add_u64 v[8:9], s[2:3], 0, v[0:1]
	v_cndmask_b32_e32 v0, v3, v4, vcc
	v_lshl_add_u64 v[8:9], v[8:9], 0, v[0:1]
	v_lshlrev_b32_e32 v0, 1, v12
	v_lshl_add_u64 v[8:9], v[8:9], 0, v[0:1]
	v_add_co_u32_e64 v8, s[4:5], s13, v8
	v_lshlrev_b32_e32 v13, 4, v7
	s_nop 0
	v_addc_co_u32_e64 v9, s[4:5], 0, v9, s[4:5]
	global_load_dwordx2 v[10:11], v[8:9], off
	v_cndmask_b32_e32 v0, v5, v6, vcc
	v_add_u32_e32 v7, s30, v7
	v_lshl_add_u64 v[8:9], s[48:49], 0, v[0:1]
	v_and_b32_e32 v0, 0x3fc00, v13
	v_cmp_lt_i32_e64 s[4:5], s14, v7
	v_lshl_add_u64 v[8:9], v[8:9], 0, v[0:1]
	v_lshlrev_b32_e32 v0, 2, v12
	v_add_u32_e32 v2, s10, v2
	s_or_b64 s[8:9], s[4:5], s[8:9]
	v_lshl_add_u64 v[12:13], v[8:9], 0, v[0:1]
	s_waitcnt vmcnt(0)
	v_lshlrev_b32_e32 v8, 16, v10
	v_and_b32_e32 v9, 0xffff0000, v10
	v_lshlrev_b32_e32 v10, 16, v11
	v_and_b32_e32 v11, 0xffff0000, v11
	global_store_dwordx4 v[12:13], v[8:11], off nt
	s_andn2_b64 exec, exec, s[8:9]
	s_cbranch_execnz .LBB0_1033

.LBB0_1083:
	s_or_b64 exec, exec, s[26:27]
	v_cmp_gt_u32_e32 vcc, s65, v39
	v_mov_b32_e32 v49, v33
	v_and_b32_e32 v39, 0x3fff00, v34
	v_cndmask_b32_e32 v48, v37, v38, vcc
	v_lshl_add_u64 v[48:49], s[48:49], 0, v[48:49]
	v_lshlrev_b32_e32 v50, 2, v39
	v_mov_b32_e32 v51, v33
	v_lshl_add_u64 v[48:49], v[48:49], 0, v[50:51]
	v_lshl_add_u64 v[48:49], v[48:49], 0, v[32:33]
	s_waitcnt vmcnt(0)
	global_store_dwordx4 v[48:49], v[28:31], off nt
	s_and_saveexec_b64 s[26:27], s[4:5]
	s_cbranch_execnz .LBB0_1090
	s_or_b64 exec, exec, s[26:27]
	s_and_saveexec_b64 s[4:5], s[6:7]
	s_cbranch_execnz .LBB0_1091

.LBB0_1090:
	v_cmp_gt_u32_e32 vcc, s65, v40
	v_add_u32_e32 v30, s55, v34
	v_mov_b32_e32 v29, v33
	v_cndmask_b32_e32 v28, v37, v38, vcc
	v_and_b32_e32 v30, 0x3fff00, v30
	v_lshl_add_u64 v[28:29], s[48:49], 0, v[28:29]
	v_lshlrev_b32_e32 v30, 2, v30
	v_mov_b32_e32 v31, v33
	v_lshl_add_u64 v[28:29], v[28:29], 0, v[30:31]
	v_lshl_add_u64 v[28:29], v[28:29], 0, v[32:33]
	global_store_dwordx4 v[28:29], v[0:3], off nt
	s_or_b64 exec, exec, s[26:27]
	s_and_saveexec_b64 s[4:5], s[6:7]
	s_cbranch_execz .LBB0_1085
.LBB0_1091:
	v_cmp_gt_u32_e32 vcc, s65, v42
	v_add_u32_e32 v30, s35, v34
	v_mov_b32_e32 v29, v33
	v_cndmask_b32_e32 v28, v37, v38, vcc
	v_and_b32_e32 v30, 0x3fff00, v30
	v_lshl_add_u64 v[28:29], s[48:49], 0, v[28:29]
	v_lshlrev_b32_e32 v30, 2, v30
	v_mov_b32_e32 v31, v33
	v_lshl_add_u64 v[28:29], v[28:29], 0, v[30:31]
	v_lshl_add_u64 v[28:29], v[28:29], 0, v[32:33]
	global_store_dwordx4 v[28:29], v[4:7], off nt
	s_or_b64 exec, exec, s[4:5]
	s_and_saveexec_b64 s[4:5], s[8:9]
	s_cbranch_execz .LBB0_1086
.LBB0_1092:
	v_cmp_gt_u32_e32 vcc, s65, v43
	v_add_u32_e32 v30, s54, v34
	v_mov_b32_e32 v29, v33
	v_cndmask_b32_e32 v28, v37, v38, vcc
	v_and_b32_e32 v30, 0x3fff00, v30
	v_lshl_add_u64 v[28:29], s[48:49], 0, v[28:29]
	v_lshlrev_b32_e32 v30, 2, v30
	v_mov_b32_e32 v31, v33
	v_lshl_add_u64 v[28:29], v[28:29], 0, v[30:31]
	v_lshl_add_u64 v[28:29], v[28:29], 0, v[32:33]
	global_store_dwordx4 v[28:29], v[8:11], off nt
	s_or_b64 exec, exec, s[4:5]
	s_and_saveexec_b64 s[4:5], s[10:11]
	s_cbranch_execz .LBB0_1087
.LBB0_1093:
	v_cmp_gt_u32_e32 vcc, s65, v44
	v_add_u32_e32 v30, s56, v34
	v_mov_b32_e32 v29, v33
	v_cndmask_b32_e32 v28, v37, v38, vcc
	v_and_b32_e32 v30, 0x3fff00, v30
	v_lshl_add_u64 v[28:29], s[48:49], 0, v[28:29]
	v_lshlrev_b32_e32 v30, 2, v30
	v_mov_b32_e32 v31, v33
	v_lshl_add_u64 v[28:29], v[28:29], 0, v[30:31]
	v_lshl_add_u64 v[28:29], v[28:29], 0, v[32:33]
	global_store_dwordx4 v[28:29], v[12:15], off nt
	s_or_b64 exec, exec, s[4:5]
	s_and_saveexec_b64 s[4:5], s[12:13]
	s_cbranch_execz .LBB0_1088
.LBB0_1094:
	v_cmp_gt_u32_e32 vcc, s65, v45
	v_add_u32_e32 v30, s58, v34
	v_mov_b32_e32 v29, v33
	v_cndmask_b32_e32 v28, v37, v38, vcc
	v_and_b32_e32 v30, 0x3fff00, v30
	v_lshl_add_u64 v[28:29], s[48:49], 0, v[28:29]
	v_lshlrev_b32_e32 v30, 2, v30
	v_mov_b32_e32 v31, v33
	v_lshl_add_u64 v[28:29], v[28:29], 0, v[30:31]
	v_lshl_add_u64 v[28:29], v[28:29], 0, v[32:33]
	global_store_dwordx4 v[28:29], v[16:19], off nt
	s_or_b64 exec, exec, s[4:5]
	s_and_saveexec_b64 s[4:5], s[14:15]
	s_cbranch_execz .LBB0_1089
.LBB0_1095:
	v_cmp_gt_u32_e32 vcc, s65, v46
	v_add_u32_e32 v30, s60, v34
	v_mov_b32_e32 v29, v33
	v_cndmask_b32_e32 v28, v37, v38, vcc
	v_and_b32_e32 v30, 0x3fff00, v30
	v_lshl_add_u64 v[28:29], s[48:49], 0, v[28:29]
	v_lshlrev_b32_e32 v30, 2, v30
	v_mov_b32_e32 v31, v33
	v_lshl_add_u64 v[28:29], v[28:29], 0, v[30:31]
	v_lshl_add_u64 v[28:29], v[28:29], 0, v[32:33]
	global_store_dwordx4 v[28:29], v[20:23], off nt
	s_or_b64 exec, exec, s[4:5]
	s_and_saveexec_b64 s[4:5], s[16:17]
	s_cbranch_execz .LBB0_1036
.LBB0_1096:
	v_cmp_gt_u32_e32 vcc, s65, v47
	v_add_u32_e32 v30, s62, v34
	v_mov_b32_e32 v29, v33
	v_cndmask_b32_e32 v28, v37, v38, vcc
	v_and_b32_e32 v30, 0x3fff00, v30
	v_lshl_add_u64 v[28:29], s[48:49], 0, v[28:29]
	v_lshlrev_b32_e32 v30, 2, v30
	v_mov_b32_e32 v31, v33
	v_lshl_add_u64 v[28:29], v[28:29], 0, v[30:31]
	v_lshl_add_u64 v[28:29], v[28:29], 0, v[32:33]
	global_store_dwordx4 v[28:29], v[24:27], off nt
	s_branch .LBB0_1036
